# v4 plus hand-written P2 H rows and deferred LayerNorm-stat scaling in gmlp_load (removes two vmcnt(0) round trips)
# speedup vs baseline: 1.0179x; 1.0014x over previous
; #define LAS __attribute__((address_space(3)))
; __device__ __forceinline__ void p2_from_regs(const Args& a, const Ctx& C, const HRow& x0, const HRow& x1, const HRow& x2, const HRow& x3) {
;     const int j = C.vcu - 128, cond = j >> 6, r0 = 32 * j + 4 * C.wave;
;     LAS f32x4* GSL = (LAS f32x4*)C.lds; LAS f32x4* SHL = GSL + 512;
;     const float* MOD = (const float*)(a.ws + WS_MOD);
;     const f32x4 g4 = ((const f32x4*)a.in[I_GPRE])[C.tid], sc4 = ((const f32x4*)(MOD + (size_t)cond * 6144 + DM))[C.tid], sh4 = ((const f32x4*)(MOD + (size_t)cond * 6144))[C.tid];
;     GSL[C.tid] = g4 * (sc4 + 1.0f); SHL[C.tid] = sh4;
;     __syncthreads();
;     bf16* H = (bf16*)(a.ws + WS_H); unsigned char* H8 = a.ws + WS_H8; float* XR = (float*)(a.ws + WS_XRMS);
;     h_store_tab<true>(x0, GSL, SHL, H + (size_t)(r0 + 0) * DM, H8 + (size_t)(r0 + 0) * DM, C.lane, XR + r0 + 0);
;     h_store_tab<true>(x1, GSL, SHL, H + (size_t)(r0 + 1) * DM, H8 + (size_t)(r0 + 1) * DM, C.lane, XR + r0 + 1);
;     h_store_tab<true>(x2, GSL, SHL, H + (size_t)(r0 + 2) * DM, H8 + (size_t)(r0 + 2) * DM, C.lane, XR + r0 + 2);
;     h_store_tab<true>(x3, GSL, SHL, H + (size_t)(r0 + 3) * DM, H8 + (size_t)(r0 + 3) * DM, C.lane, XR + r0 + 3);
.LBB0_296:
	s_andn2_b64 vcc, exec, s[6:7]
	s_cbranch_vccnz .LBB0_309
	s_addk_i32 s0, 0xff80
	s_lshr_b32 s1, s0, 6
	s_lshl_b32 s2, s0, 5
	s_lshl_b32 s4, s82, 2
	s_add_i32 s4, s2, s4
	s_mul_i32 s1, s1, 0x6000
	s_add_u32 s6, s94, s1
	s_addc_u32 s7, s95, 0
	s_add_u32 s6, s6, 0x1f00000
	s_addc_u32 s7, s7, 0
	s_add_u32 s24, s6, 0x2000
	s_addc_u32 s25, s7, 0
	v_lshlrev_b32_e32 v132, 4, v0
	v_lshlrev_b32_e32 v133, 4, v162
	v_mov_b32_e32 v131, 0
	v_mov_b32_e32 v160, 0x43e00000
	v_mov_b32_e32 v161, 0x358637bd
	s_mov_b32 s33, 0xc3e00000
	global_load_dwordx4 v[140:143], v132, s[12:13]
	global_load_dwordx4 v[144:147], v132, s[24:25]
	global_load_dwordx4 v[148:151], v132, s[6:7]
	s_lshl_b32 s2, s4, 2
	s_add_u32 s36, s94, s2
	s_addc_u32 s37, s95, 0
	s_add_u32 s36, s36, 0x22c0000
	s_addc_u32 s37, s37, 0
	v_cmp_eq_u32_e64 s[72:73], 0, v162
	v_lshrrev_b32_e32 v246, 1, v133
	v_lshrrev_b32_e32 v247, 2, v133
	s_lshl_b32 s29, s4, 12
	s_add_u32 s44, s94, s29
	s_addc_u32 s45, s95, 0
	s_add_u32 s44, s44, 0x2400000
	s_addc_u32 s45, s45, 0
	s_lshr_b32 s29, s29, 1
	s_add_u32 s52, s94, s29
	s_addc_u32 s53, s95, 0
	s_add_u32 s52, s52, 0xe500000
	s_addc_u32 s53, s53, 0
	s_add_i32 s5, s4, 1
	s_lshl_b32 s29, s5, 12
	s_add_u32 s46, s94, s29
	s_addc_u32 s47, s95, 0
	s_add_u32 s46, s46, 0x2400000
	s_addc_u32 s47, s47, 0
	s_lshr_b32 s29, s29, 1
	s_add_u32 s54, s94, s29
	s_addc_u32 s55, s95, 0
	s_add_u32 s54, s54, 0xe500000
	s_addc_u32 s55, s55, 0
	s_add_i32 s5, s4, 2
	s_lshl_b32 s29, s5, 12
	s_add_u32 s48, s94, s29
	s_addc_u32 s49, s95, 0
	s_add_u32 s48, s48, 0x2400000
	s_addc_u32 s49, s49, 0
	s_lshr_b32 s29, s29, 1
	s_add_u32 s60, s94, s29
	s_addc_u32 s61, s95, 0
	s_add_u32 s60, s60, 0xe500000
	s_addc_u32 s61, s61, 0
	s_add_i32 s5, s4, 3
	s_lshl_b32 s29, s5, 12
	s_add_u32 s50, s94, s29
	s_addc_u32 s51, s95, 0
	s_add_u32 s50, s50, 0x2400000
	s_addc_u32 s51, s51, 0
	s_lshr_b32 s29, s29, 1
	s_add_u32 s62, s94, s29
	s_addc_u32 s63, s95, 0
	s_add_u32 s62, s62, 0xe500000
	s_addc_u32 s63, s63, 0
	v_mul_f32_e32 v202, v127, v127
	v_mul_f32_e32 v210, v129, v129
	v_fmac_f32_e32 v202, v126, v126
	v_fmac_f32_e32 v210, v128, v128
	v_add_f32_e32 v202, v202, v210
	v_mul_f32_e32 v203, v123, v123
	v_mul_f32_e32 v210, v125, v125
	v_fmac_f32_e32 v203, v122, v122
	v_fmac_f32_e32 v210, v124, v124
	v_add_f32_e32 v203, v203, v210
	v_add_f32_e32 v202, v202, v203
	v_mul_f32_e32 v203, v119, v119
	v_mul_f32_e32 v210, v121, v121
	v_fmac_f32_e32 v203, v118, v118
	v_fmac_f32_e32 v210, v120, v120
	v_add_f32_e32 v203, v203, v210
	v_add_f32_e32 v202, v202, v203
	v_mul_f32_e32 v203, v115, v115
	v_mul_f32_e32 v210, v117, v117
	v_fmac_f32_e32 v203, v114, v114
	v_fmac_f32_e32 v210, v116, v116
	v_add_f32_e32 v203, v203, v210
	v_add_f32_e32 v202, v202, v203
	v_mul_f32_e32 v203, v111, v111
	v_mul_f32_e32 v210, v113, v113
	v_fmac_f32_e32 v203, v110, v110
	v_fmac_f32_e32 v210, v112, v112
	v_add_f32_e32 v203, v203, v210
	v_add_f32_e32 v202, v202, v203
	v_mul_f32_e32 v203, v107, v107
	v_mul_f32_e32 v210, v109, v109
	v_fmac_f32_e32 v203, v106, v106
	v_fmac_f32_e32 v210, v108, v108
	v_add_f32_e32 v203, v203, v210
	v_add_f32_e32 v202, v202, v203
	v_mul_f32_e32 v203, v103, v103
	v_mul_f32_e32 v210, v105, v105
	v_fmac_f32_e32 v203, v102, v102
	v_fmac_f32_e32 v210, v104, v104
	v_add_f32_e32 v203, v203, v210
	v_add_f32_e32 v202, v202, v203
	v_mul_f32_e32 v203, v99, v99
	v_mul_f32_e32 v210, v101, v101
	v_fmac_f32_e32 v203, v98, v98
	v_fmac_f32_e32 v210, v100, v100
	v_add_f32_e32 v203, v203, v210
	v_add_f32_e32 v202, v202, v203
	v_mul_f32_e32 v204, v95, v95
	v_mul_f32_e32 v211, v97, v97
	v_fmac_f32_e32 v204, v94, v94
	v_fmac_f32_e32 v211, v96, v96
	v_add_f32_e32 v204, v204, v211
	v_mul_f32_e32 v205, v91, v91
	v_mul_f32_e32 v211, v93, v93
	v_fmac_f32_e32 v205, v90, v90
	v_fmac_f32_e32 v211, v92, v92
	v_add_f32_e32 v205, v205, v211
	v_add_f32_e32 v204, v204, v205
	v_mul_f32_e32 v205, v87, v87
	v_mul_f32_e32 v211, v89, v89
	v_fmac_f32_e32 v205, v86, v86
	v_fmac_f32_e32 v211, v88, v88
	v_add_f32_e32 v205, v205, v211
	v_add_f32_e32 v204, v204, v205
	v_mul_f32_e32 v205, v83, v83
	v_mul_f32_e32 v211, v85, v85
	v_fmac_f32_e32 v205, v82, v82
	v_fmac_f32_e32 v211, v84, v84
	v_add_f32_e32 v205, v205, v211
	v_add_f32_e32 v204, v204, v205
	v_mul_f32_e32 v205, v79, v79
	v_mul_f32_e32 v211, v81, v81
	v_fmac_f32_e32 v205, v78, v78
	v_fmac_f32_e32 v211, v80, v80
	v_add_f32_e32 v205, v205, v211
	v_add_f32_e32 v204, v204, v205
	v_mul_f32_e32 v205, v75, v75
	v_mul_f32_e32 v211, v77, v77
	v_fmac_f32_e32 v205, v74, v74
	v_fmac_f32_e32 v211, v76, v76
	v_add_f32_e32 v205, v205, v211
	v_add_f32_e32 v204, v204, v205
	v_mul_f32_e32 v205, v71, v71
	v_mul_f32_e32 v211, v73, v73
	v_fmac_f32_e32 v205, v70, v70
	v_fmac_f32_e32 v211, v72, v72
	v_add_f32_e32 v205, v205, v211
	v_add_f32_e32 v204, v204, v205
	v_mul_f32_e32 v205, v67, v67
	v_mul_f32_e32 v211, v69, v69
	v_fmac_f32_e32 v205, v66, v66
	v_fmac_f32_e32 v211, v68, v68
	v_add_f32_e32 v205, v205, v211
	v_add_f32_e32 v204, v204, v205
	v_mul_f32_e32 v206, v63, v63
	v_mul_f32_e32 v212, v65, v65
	v_fmac_f32_e32 v206, v62, v62
	v_fmac_f32_e32 v212, v64, v64
	v_add_f32_e32 v206, v206, v212
	v_mul_f32_e32 v207, v59, v59
	v_mul_f32_e32 v212, v61, v61
	v_fmac_f32_e32 v207, v58, v58
	v_fmac_f32_e32 v212, v60, v60
	v_add_f32_e32 v207, v207, v212
	v_add_f32_e32 v206, v206, v207
	v_mul_f32_e32 v207, v55, v55
	v_mul_f32_e32 v212, v57, v57
	v_fmac_f32_e32 v207, v54, v54
	v_fmac_f32_e32 v212, v56, v56
	v_add_f32_e32 v207, v207, v212
	v_add_f32_e32 v206, v206, v207
	v_mul_f32_e32 v207, v51, v51
	v_mul_f32_e32 v212, v53, v53
	v_fmac_f32_e32 v207, v50, v50
	v_fmac_f32_e32 v212, v52, v52
	v_add_f32_e32 v207, v207, v212
; #define LAS __attribute__((address_space(3)))
; template <bool WT = true> __device__ __forceinline__ void h_store_tab(const HRow& X, const LAS f32x4* GS, const LAS f32x4* SH, bf16* hrow, unsigned char* h8row, int lane, float* rms_slot) {
;     float ss = 0.f;
; #pragma unroll
;     for (int j = 0; j < 8; ++j) ss += (X.v[j][0] * X.v[j][0] + X.v[j][1] * X.v[j][1]) + (X.v[j][2] * X.v[j][2] + X.v[j][3] * X.v[j][3]);
;     const float ms = wave_sum(ss) * (1.0f / DM) + EPS, rr = __builtin_amdgcn_rsqf(ms);
;     if (lane == 0) *rms_slot = ms * rr;
; __device__ __forceinline__ void p2_from_regs(const Args& a, const Ctx& C, const HRow& x0, const HRow& x1, const HRow& x2, const HRow& x3) {
;     ...
;     const f32x4 g4 = ((const f32x4*)a.in[I_GPRE])[C.tid], sc4 = ((const f32x4*)(MOD + (size_t)cond * 6144 + DM))[C.tid], sh4 = ((const f32x4*)(MOD + (size_t)cond * 6144))[C.tid];
;     GSL[C.tid] = g4 * (sc4 + 1.0f); SHL[C.tid] = sh4;
;     __syncthreads();
	v_add_f32_e32 v206, v206, v207
	v_mul_f32_e32 v207, v47, v47
	v_mul_f32_e32 v212, v49, v49
	v_fmac_f32_e32 v207, v46, v46
	v_fmac_f32_e32 v212, v48, v48
	v_add_f32_e32 v207, v207, v212
	v_add_f32_e32 v206, v206, v207
	v_mul_f32_e32 v207, v43, v43
	v_mul_f32_e32 v212, v45, v45
	v_fmac_f32_e32 v207, v42, v42
	v_fmac_f32_e32 v212, v44, v44
	v_add_f32_e32 v207, v207, v212
	v_add_f32_e32 v206, v206, v207
	v_mul_f32_e32 v207, v39, v39
	v_mul_f32_e32 v212, v41, v41
	v_fmac_f32_e32 v207, v38, v38
	v_fmac_f32_e32 v212, v40, v40
	v_add_f32_e32 v207, v207, v212
	v_add_f32_e32 v206, v206, v207
	v_mul_f32_e32 v207, v35, v35
	v_mul_f32_e32 v212, v37, v37
	v_fmac_f32_e32 v207, v34, v34
	v_fmac_f32_e32 v212, v36, v36
	v_add_f32_e32 v207, v207, v212
	v_add_f32_e32 v206, v206, v207
	v_mul_f32_e32 v208, v31, v31
	v_mul_f32_e32 v213, v33, v33
	v_fmac_f32_e32 v208, v30, v30
	v_fmac_f32_e32 v213, v32, v32
	v_add_f32_e32 v208, v208, v213
	v_mul_f32_e32 v209, v27, v27
	v_mul_f32_e32 v213, v29, v29
	v_fmac_f32_e32 v209, v26, v26
	v_fmac_f32_e32 v213, v28, v28
	v_add_f32_e32 v209, v209, v213
	v_add_f32_e32 v208, v208, v209
	v_mul_f32_e32 v209, v23, v23
	v_mul_f32_e32 v213, v25, v25
	v_fmac_f32_e32 v209, v22, v22
	v_fmac_f32_e32 v213, v24, v24
	v_add_f32_e32 v209, v209, v213
	v_add_f32_e32 v208, v208, v209
	v_mul_f32_e32 v209, v19, v19
	v_mul_f32_e32 v213, v21, v21
	v_fmac_f32_e32 v209, v18, v18
	v_fmac_f32_e32 v213, v20, v20
	v_add_f32_e32 v209, v209, v213
	v_add_f32_e32 v208, v208, v209
	v_mul_f32_e32 v209, v15, v15
	v_mul_f32_e32 v213, v17, v17
	v_fmac_f32_e32 v209, v14, v14
	v_fmac_f32_e32 v213, v16, v16
	v_add_f32_e32 v209, v209, v213
	v_add_f32_e32 v208, v208, v209
	v_mul_f32_e32 v209, v11, v11
	v_mul_f32_e32 v213, v13, v13
	v_fmac_f32_e32 v209, v10, v10
	v_fmac_f32_e32 v213, v12, v12
	v_add_f32_e32 v209, v209, v213
	v_add_f32_e32 v208, v208, v209
	v_mul_f32_e32 v209, v7, v7
	v_mul_f32_e32 v213, v9, v9
	v_fmac_f32_e32 v209, v6, v6
	v_fmac_f32_e32 v213, v8, v8
	v_add_f32_e32 v209, v209, v213
	v_add_f32_e32 v208, v208, v209
	v_mul_f32_e32 v209, v3, v3
	v_mul_f32_e32 v213, v5, v5
	v_fmac_f32_e32 v209, v2, v2
	v_fmac_f32_e32 v213, v4, v4
	v_add_f32_e32 v209, v209, v213
	v_add_f32_e32 v208, v208, v209
	s_nop 1
	v_add_f32_dpp v202, v202, v202 quad_perm:[1,0,3,2] row_mask:0xf bank_mask:0xf
	v_add_f32_dpp v204, v204, v204 quad_perm:[1,0,3,2] row_mask:0xf bank_mask:0xf
	v_add_f32_dpp v206, v206, v206 quad_perm:[1,0,3,2] row_mask:0xf bank_mask:0xf
	v_add_f32_dpp v208, v208, v208 quad_perm:[1,0,3,2] row_mask:0xf bank_mask:0xf
	v_add_f32_dpp v202, v202, v202 quad_perm:[2,3,0,1] row_mask:0xf bank_mask:0xf
	v_add_f32_dpp v204, v204, v204 quad_perm:[2,3,0,1] row_mask:0xf bank_mask:0xf
	v_add_f32_dpp v206, v206, v206 quad_perm:[2,3,0,1] row_mask:0xf bank_mask:0xf
	v_add_f32_dpp v208, v208, v208 quad_perm:[2,3,0,1] row_mask:0xf bank_mask:0xf
	v_add_f32_dpp v202, v202, v202 row_half_mirror row_mask:0xf bank_mask:0xf
	v_add_f32_dpp v204, v204, v204 row_half_mirror row_mask:0xf bank_mask:0xf
	v_add_f32_dpp v206, v206, v206 row_half_mirror row_mask:0xf bank_mask:0xf
	v_add_f32_dpp v208, v208, v208 row_half_mirror row_mask:0xf bank_mask:0xf
	v_add_f32_dpp v202, v202, v202 row_mirror row_mask:0xf bank_mask:0xf
	v_add_f32_dpp v204, v204, v204 row_mirror row_mask:0xf bank_mask:0xf
	v_add_f32_dpp v206, v206, v206 row_mirror row_mask:0xf bank_mask:0xf
	v_add_f32_dpp v208, v208, v208 row_mirror row_mask:0xf bank_mask:0xf
	v_mov_b32_e32 v203, v202
	v_mov_b32_e32 v205, v204
	v_mov_b32_e32 v207, v206
	v_mov_b32_e32 v209, v208
	s_nop 1
	v_permlane16_swap_b32_e32 v203, v202
	v_permlane16_swap_b32_e32 v205, v204
	v_permlane16_swap_b32_e32 v207, v206
	v_permlane16_swap_b32_e32 v209, v208
	s_nop 1
	v_add_f32_e32 v202, v202, v203
	v_add_f32_e32 v204, v204, v205
	v_add_f32_e32 v206, v206, v207
	v_add_f32_e32 v208, v208, v209
	v_mov_b32_e32 v203, v202
	v_mov_b32_e32 v205, v204
	v_mov_b32_e32 v207, v206
	v_mov_b32_e32 v209, v208
	s_nop 1
	v_permlane32_swap_b32_e32 v203, v202
	v_permlane32_swap_b32_e32 v205, v204
	v_permlane32_swap_b32_e32 v207, v206
	v_permlane32_swap_b32_e32 v209, v208
	s_nop 1
	v_add_f32_e32 v202, v202, v203
	v_add_f32_e32 v204, v204, v205
	v_add_f32_e32 v206, v206, v207
	v_add_f32_e32 v208, v208, v209
	v_fmamk_f32 v210, v202, 0x3a000000, v161
	v_fmamk_f32 v211, v204, 0x3a000000, v161
	v_fmamk_f32 v212, v206, 0x3a000000, v161
	v_fmamk_f32 v213, v208, 0x3a000000, v161
	v_rsq_f32_e32 v202, v210
	v_rsq_f32_e32 v204, v211
	v_rsq_f32_e32 v206, v212
	v_rsq_f32_e32 v208, v213
	s_mov_b64 s[38:39], exec
	s_mov_b64 exec, s[72:73]
	v_mul_f32_e32 v235, v210, v202
	v_mul_f32_e32 v243, v211, v204
	v_mul_f32_e32 v189, v212, v206
	v_mul_f32_e32 v192, v213, v208
	global_store_dword v131, v235, s[36:37]
	global_store_dword v131, v243, s[36:37] offset:4
	global_store_dword v131, v189, s[36:37] offset:8
	global_store_dword v131, v192, s[36:37] offset:12
	s_mov_b64 exec, s[38:39]
	s_waitcnt vmcnt(0)
	v_pk_add_f32 v[144:145], v[144:145], 1.0 op_sel_hi:[1,0]
	v_pk_add_f32 v[146:147], v[146:147], 1.0 op_sel_hi:[1,0]
	v_pk_mul_f32 v[140:141], v[140:141], v[144:145]
	v_pk_mul_f32 v[142:143], v[142:143], v[146:147]
	ds_write_b128 v132, v[140:143]
	ds_write_b128 v132, v[148:151] offset:8192
	s_waitcnt lgkmcnt(0)
	s_barrier
; #define GAS __attribute__((address_space(1)))
; __device__ __forceinline__ unsigned pk2(float lo, float hi) { return pg8::cvt_pk_bf16(lo, hi); }
; __device__ __forceinline__ unsigned pk4f8(float a, float b, float c, float d) { int p = __builtin_amdgcn_cvt_pk_fp8_f32(sat8(a), sat8(b), 0, false); p = __builtin_amdgcn_cvt_pk_fp8_f32(sat8(c), sat8(d), p, true); return (unsigned)p; }
; template <bool WT = true> __device__ __forceinline__ void h_store_tab(const HRow& X, const LAS f32x4* GS, const LAS f32x4* SH, bf16* hrow, unsigned char* h8row, int lane, float* rms_slot) {
;     ...
; #pragma unroll
;     for (int j = 0; j < 8; ++j) { const f32x4 h = X.v[j] * rr * GS[lane + 64 * j] + SH[lane + 64 * j]; const unsigned w0 = pk2(h[0], h[1]), w1 = pk2(h[2], h[3]);
;         const unsigned w8 = pk4f8(h[0], h[1], h[2], h[3]);
;         if (WT) { __hip_atomic_store((unsigned long long*)(hrow) + lane + 64 * j, ((unsigned long long)w1 << 32) | w0, RLX_AGENT); __hip_atomic_store((unsigned*)h8row + lane + 64 * j, w8, RLX_AGENT); }
;         else { ((GAS v2u*)hrow)[lane + 64 * j] = (v2u){w0, w1}; ((unsigned*)h8row)[lane + 64 * j] = w8; } }
	ds_read_b128 v[214:217], v133
	ds_read_b128 v[218:221], v133 offset:8192
	ds_read_b128 v[222:225], v133 offset:1024
	ds_read_b128 v[226:229], v133 offset:9216
	s_waitcnt lgkmcnt(2)
	v_pk_mul_f32 v[126:127], v[126:127], v[202:203] op_sel_hi:[1,0]
	v_pk_mul_f32 v[128:129], v[128:129], v[202:203] op_sel_hi:[1,0]
	v_pk_fma_f32 v[126:127], v[126:127], v[214:215], v[218:219]
	v_pk_fma_f32 v[128:129], v[128:129], v[216:217], v[220:221]
	v_med3_f32 v230, v126, s33, v160
	v_med3_f32 v231, v127, s33, v160
	v_med3_f32 v232, v128, s33, v160
	v_med3_f32 v233, v129, s33, v160
	v_cvt_pk_fp8_f32 v234, v230, v231
	v_cvt_pk_bf16_f32 v236, v126, v127
	v_cvt_pk_bf16_f32 v237, v128, v129
	v_cvt_pk_fp8_f32 v234, v232, v233 op_sel:[0,0,1]
	global_store_dwordx2 v246, v[236:237], s[44:45] sc1
	global_store_dword v247, v234, s[52:53] sc1
	v_pk_mul_f32 v[94:95], v[94:95], v[204:205] op_sel_hi:[1,0]
	v_pk_mul_f32 v[96:97], v[96:97], v[204:205] op_sel_hi:[1,0]
	v_pk_fma_f32 v[94:95], v[94:95], v[214:215], v[218:219]
	v_pk_fma_f32 v[96:97], v[96:97], v[216:217], v[220:221]
	v_med3_f32 v238, v94, s33, v160
	v_med3_f32 v239, v95, s33, v160
	v_med3_f32 v240, v96, s33, v160
	v_med3_f32 v241, v97, s33, v160
	v_cvt_pk_fp8_f32 v242, v238, v239
	v_cvt_pk_bf16_f32 v244, v94, v95
	v_cvt_pk_bf16_f32 v245, v96, v97
	v_cvt_pk_fp8_f32 v242, v240, v241 op_sel:[0,0,1]
	global_store_dwordx2 v246, v[244:245], s[46:47] sc1
	global_store_dword v247, v242, s[54:55] sc1
	v_pk_mul_f32 v[62:63], v[62:63], v[206:207] op_sel_hi:[1,0]
	v_pk_mul_f32 v[64:65], v[64:65], v[206:207] op_sel_hi:[1,0]
	v_pk_fma_f32 v[62:63], v[62:63], v[214:215], v[218:219]
	v_pk_fma_f32 v[64:65], v[64:65], v[216:217], v[220:221]
	v_med3_f32 v230, v62, s33, v160
	v_med3_f32 v231, v63, s33, v160
	v_med3_f32 v232, v64, s33, v160
	v_med3_f32 v233, v65, s33, v160
	v_cvt_pk_fp8_f32 v234, v230, v231
	v_cvt_pk_bf16_f32 v236, v62, v63
	v_cvt_pk_bf16_f32 v237, v64, v65
	v_cvt_pk_fp8_f32 v234, v232, v233 op_sel:[0,0,1]
	global_store_dwordx2 v246, v[236:237], s[48:49] sc1
	global_store_dword v247, v234, s[60:61] sc1
	v_pk_mul_f32 v[30:31], v[30:31], v[208:209] op_sel_hi:[1,0]
	v_pk_mul_f32 v[32:33], v[32:33], v[208:209] op_sel_hi:[1,0]
	v_pk_fma_f32 v[30:31], v[30:31], v[214:215], v[218:219]
	v_pk_fma_f32 v[32:33], v[32:33], v[216:217], v[220:221]
	v_med3_f32 v238, v30, s33, v160
	v_med3_f32 v239, v31, s33, v160
	v_med3_f32 v240, v32, s33, v160
	v_med3_f32 v241, v33, s33, v160
	v_cvt_pk_fp8_f32 v242, v238, v239
	v_cvt_pk_bf16_f32 v244, v30, v31
	v_cvt_pk_bf16_f32 v245, v32, v33
	v_cvt_pk_fp8_f32 v242, v240, v241 op_sel:[0,0,1]
	global_store_dwordx2 v246, v[244:245], s[50:51] sc1
	global_store_dword v247, v242, s[62:63] sc1
	ds_read_b128 v[214:217], v133 offset:2048
	ds_read_b128 v[218:221], v133 offset:10240
	s_waitcnt lgkmcnt(2)
	v_pk_mul_f32 v[122:123], v[122:123], v[202:203] op_sel_hi:[1,0]
	v_pk_mul_f32 v[124:125], v[124:125], v[202:203] op_sel_hi:[1,0]
	v_pk_fma_f32 v[122:123], v[122:123], v[222:223], v[226:227]
	v_pk_fma_f32 v[124:125], v[124:125], v[224:225], v[228:229]
	v_med3_f32 v230, v122, s33, v160
	v_med3_f32 v231, v123, s33, v160
	v_med3_f32 v232, v124, s33, v160
	v_med3_f32 v233, v125, s33, v160
	v_cvt_pk_fp8_f32 v234, v230, v231
	v_cvt_pk_bf16_f32 v236, v122, v123
	v_cvt_pk_bf16_f32 v237, v124, v125
	v_cvt_pk_fp8_f32 v234, v232, v233 op_sel:[0,0,1]
	global_store_dwordx2 v246, v[236:237], s[44:45] offset:512 sc1
	global_store_dword v247, v234, s[52:53] offset:256 sc1
	v_pk_mul_f32 v[90:91], v[90:91], v[204:205] op_sel_hi:[1,0]
	v_pk_mul_f32 v[92:93], v[92:93], v[204:205] op_sel_hi:[1,0]
	v_pk_fma_f32 v[90:91], v[90:91], v[222:223], v[226:227]
	v_pk_fma_f32 v[92:93], v[92:93], v[224:225], v[228:229]
	v_med3_f32 v238, v90, s33, v160
	v_med3_f32 v239, v91, s33, v160
	v_med3_f32 v240, v92, s33, v160
	v_med3_f32 v241, v93, s33, v160
	v_cvt_pk_fp8_f32 v242, v238, v239
	v_cvt_pk_bf16_f32 v244, v90, v91
	v_cvt_pk_bf16_f32 v245, v92, v93
	v_cvt_pk_fp8_f32 v242, v240, v241 op_sel:[0,0,1]
	global_store_dwordx2 v246, v[244:245], s[46:47] offset:512 sc1
	global_store_dword v247, v242, s[54:55] offset:256 sc1
	v_pk_mul_f32 v[58:59], v[58:59], v[206:207] op_sel_hi:[1,0]
	v_pk_mul_f32 v[60:61], v[60:61], v[206:207] op_sel_hi:[1,0]
	v_pk_fma_f32 v[58:59], v[58:59], v[222:223], v[226:227]
	v_pk_fma_f32 v[60:61], v[60:61], v[224:225], v[228:229]
	v_med3_f32 v230, v58, s33, v160
	v_med3_f32 v231, v59, s33, v160
	v_med3_f32 v232, v60, s33, v160
	v_med3_f32 v233, v61, s33, v160
	v_cvt_pk_fp8_f32 v234, v230, v231
	v_cvt_pk_bf16_f32 v236, v58, v59
	v_cvt_pk_bf16_f32 v237, v60, v61
	v_cvt_pk_fp8_f32 v234, v232, v233 op_sel:[0,0,1]
	global_store_dwordx2 v246, v[236:237], s[48:49] offset:512 sc1
	global_store_dword v247, v234, s[60:61] offset:256 sc1
	v_pk_mul_f32 v[26:27], v[26:27], v[208:209] op_sel_hi:[1,0]
	v_pk_mul_f32 v[28:29], v[28:29], v[208:209] op_sel_hi:[1,0]
	v_pk_fma_f32 v[26:27], v[26:27], v[222:223], v[226:227]
	v_pk_fma_f32 v[28:29], v[28:29], v[224:225], v[228:229]
	v_med3_f32 v238, v26, s33, v160
	v_med3_f32 v239, v27, s33, v160
	v_med3_f32 v240, v28, s33, v160
	v_med3_f32 v241, v29, s33, v160
	v_cvt_pk_fp8_f32 v242, v238, v239
	v_cvt_pk_bf16_f32 v244, v26, v27
	v_cvt_pk_bf16_f32 v245, v28, v29
	v_cvt_pk_fp8_f32 v242, v240, v241 op_sel:[0,0,1]
	global_store_dwordx2 v246, v[244:245], s[50:51] offset:512 sc1
	global_store_dword v247, v242, s[62:63] offset:256 sc1
	ds_read_b128 v[222:225], v133 offset:3072
	ds_read_b128 v[226:229], v133 offset:11264
	s_waitcnt lgkmcnt(2)
; #define GAS __attribute__((address_space(1)))
; __device__ __forceinline__ unsigned pk2(float lo, float hi) { return pg8::cvt_pk_bf16(lo, hi); }
; __device__ __forceinline__ unsigned pk4f8(float a, float b, float c, float d) { int p = __builtin_amdgcn_cvt_pk_fp8_f32(sat8(a), sat8(b), 0, false); p = __builtin_amdgcn_cvt_pk_fp8_f32(sat8(c), sat8(d), p, true); return (unsigned)p; }
; template <bool WT = true> __device__ __forceinline__ void h_store_tab(const HRow& X, const LAS f32x4* GS, const LAS f32x4* SH, bf16* hrow, unsigned char* h8row, int lane, float* rms_slot) {
;     ...
; #pragma unroll
;     for (int j = 0; j < 8; ++j) { const f32x4 h = X.v[j] * rr * GS[lane + 64 * j] + SH[lane + 64 * j]; const unsigned w0 = pk2(h[0], h[1]), w1 = pk2(h[2], h[3]);
;         const unsigned w8 = pk4f8(h[0], h[1], h[2], h[3]);
;         if (WT) { __hip_atomic_store((unsigned long long*)(hrow) + lane + 64 * j, ((unsigned long long)w1 << 32) | w0, RLX_AGENT); __hip_atomic_store((unsigned*)h8row + lane + 64 * j, w8, RLX_AGENT); }
;         else { ((GAS v2u*)hrow)[lane + 64 * j] = (v2u){w0, w1}; ((unsigned*)h8row)[lane + 64 * j] = w8; } }
	v_pk_mul_f32 v[118:119], v[118:119], v[202:203] op_sel_hi:[1,0]
	v_pk_mul_f32 v[120:121], v[120:121], v[202:203] op_sel_hi:[1,0]
	v_pk_fma_f32 v[118:119], v[118:119], v[214:215], v[218:219]
	v_pk_fma_f32 v[120:121], v[120:121], v[216:217], v[220:221]
	v_med3_f32 v230, v118, s33, v160
	v_med3_f32 v231, v119, s33, v160
	v_med3_f32 v232, v120, s33, v160
	v_med3_f32 v233, v121, s33, v160
	v_cvt_pk_fp8_f32 v234, v230, v231
	v_cvt_pk_bf16_f32 v236, v118, v119
	v_cvt_pk_bf16_f32 v237, v120, v121
	v_cvt_pk_fp8_f32 v234, v232, v233 op_sel:[0,0,1]
	global_store_dwordx2 v246, v[236:237], s[44:45] offset:1024 sc1
	global_store_dword v247, v234, s[52:53] offset:512 sc1
	v_pk_mul_f32 v[86:87], v[86:87], v[204:205] op_sel_hi:[1,0]
	v_pk_mul_f32 v[88:89], v[88:89], v[204:205] op_sel_hi:[1,0]
	v_pk_fma_f32 v[86:87], v[86:87], v[214:215], v[218:219]
	v_pk_fma_f32 v[88:89], v[88:89], v[216:217], v[220:221]
	v_med3_f32 v238, v86, s33, v160
	v_med3_f32 v239, v87, s33, v160
	v_med3_f32 v240, v88, s33, v160
	v_med3_f32 v241, v89, s33, v160
	v_cvt_pk_fp8_f32 v242, v238, v239
	v_cvt_pk_bf16_f32 v244, v86, v87
	v_cvt_pk_bf16_f32 v245, v88, v89
	v_cvt_pk_fp8_f32 v242, v240, v241 op_sel:[0,0,1]
	global_store_dwordx2 v246, v[244:245], s[46:47] offset:1024 sc1
	global_store_dword v247, v242, s[54:55] offset:512 sc1
	v_pk_mul_f32 v[54:55], v[54:55], v[206:207] op_sel_hi:[1,0]
	v_pk_mul_f32 v[56:57], v[56:57], v[206:207] op_sel_hi:[1,0]
	v_pk_fma_f32 v[54:55], v[54:55], v[214:215], v[218:219]
	v_pk_fma_f32 v[56:57], v[56:57], v[216:217], v[220:221]
	v_med3_f32 v230, v54, s33, v160
	v_med3_f32 v231, v55, s33, v160
	v_med3_f32 v232, v56, s33, v160
	v_med3_f32 v233, v57, s33, v160
	v_cvt_pk_fp8_f32 v234, v230, v231
	v_cvt_pk_bf16_f32 v236, v54, v55
	v_cvt_pk_bf16_f32 v237, v56, v57
	v_cvt_pk_fp8_f32 v234, v232, v233 op_sel:[0,0,1]
	global_store_dwordx2 v246, v[236:237], s[48:49] offset:1024 sc1
	global_store_dword v247, v234, s[60:61] offset:512 sc1
	v_pk_mul_f32 v[22:23], v[22:23], v[208:209] op_sel_hi:[1,0]
	v_pk_mul_f32 v[24:25], v[24:25], v[208:209] op_sel_hi:[1,0]
	v_pk_fma_f32 v[22:23], v[22:23], v[214:215], v[218:219]
	v_pk_fma_f32 v[24:25], v[24:25], v[216:217], v[220:221]
	v_med3_f32 v238, v22, s33, v160
	v_med3_f32 v239, v23, s33, v160
	v_med3_f32 v240, v24, s33, v160
	v_med3_f32 v241, v25, s33, v160
	v_cvt_pk_fp8_f32 v242, v238, v239
	v_cvt_pk_bf16_f32 v244, v22, v23
	v_cvt_pk_bf16_f32 v245, v24, v25
	v_cvt_pk_fp8_f32 v242, v240, v241 op_sel:[0,0,1]
	global_store_dwordx2 v246, v[244:245], s[50:51] offset:1024 sc1
	global_store_dword v247, v242, s[62:63] offset:512 sc1
	ds_read_b128 v[214:217], v133 offset:4096
	ds_read_b128 v[218:221], v133 offset:12288
	s_waitcnt lgkmcnt(2)
	v_pk_mul_f32 v[114:115], v[114:115], v[202:203] op_sel_hi:[1,0]
	v_pk_mul_f32 v[116:117], v[116:117], v[202:203] op_sel_hi:[1,0]
	v_pk_fma_f32 v[114:115], v[114:115], v[222:223], v[226:227]
	v_pk_fma_f32 v[116:117], v[116:117], v[224:225], v[228:229]
	v_med3_f32 v230, v114, s33, v160
	v_med3_f32 v231, v115, s33, v160
	v_med3_f32 v232, v116, s33, v160
	v_med3_f32 v233, v117, s33, v160
	v_cvt_pk_fp8_f32 v234, v230, v231
	v_cvt_pk_bf16_f32 v236, v114, v115
	v_cvt_pk_bf16_f32 v237, v116, v117
	v_cvt_pk_fp8_f32 v234, v232, v233 op_sel:[0,0,1]
	global_store_dwordx2 v246, v[236:237], s[44:45] offset:1536 sc1
	global_store_dword v247, v234, s[52:53] offset:768 sc1
	v_pk_mul_f32 v[82:83], v[82:83], v[204:205] op_sel_hi:[1,0]
	v_pk_mul_f32 v[84:85], v[84:85], v[204:205] op_sel_hi:[1,0]
	v_pk_fma_f32 v[82:83], v[82:83], v[222:223], v[226:227]
	v_pk_fma_f32 v[84:85], v[84:85], v[224:225], v[228:229]
	v_med3_f32 v238, v82, s33, v160
	v_med3_f32 v239, v83, s33, v160
	v_med3_f32 v240, v84, s33, v160
	v_med3_f32 v241, v85, s33, v160
	v_cvt_pk_fp8_f32 v242, v238, v239
	v_cvt_pk_bf16_f32 v244, v82, v83
	v_cvt_pk_bf16_f32 v245, v84, v85
	v_cvt_pk_fp8_f32 v242, v240, v241 op_sel:[0,0,1]
	global_store_dwordx2 v246, v[244:245], s[46:47] offset:1536 sc1
	global_store_dword v247, v242, s[54:55] offset:768 sc1
	v_pk_mul_f32 v[50:51], v[50:51], v[206:207] op_sel_hi:[1,0]
	v_pk_mul_f32 v[52:53], v[52:53], v[206:207] op_sel_hi:[1,0]
	v_pk_fma_f32 v[50:51], v[50:51], v[222:223], v[226:227]
	v_pk_fma_f32 v[52:53], v[52:53], v[224:225], v[228:229]
	v_med3_f32 v230, v50, s33, v160
	v_med3_f32 v231, v51, s33, v160
	v_med3_f32 v232, v52, s33, v160
	v_med3_f32 v233, v53, s33, v160
	v_cvt_pk_fp8_f32 v234, v230, v231
	v_cvt_pk_bf16_f32 v236, v50, v51
	v_cvt_pk_bf16_f32 v237, v52, v53
	v_cvt_pk_fp8_f32 v234, v232, v233 op_sel:[0,0,1]
	global_store_dwordx2 v246, v[236:237], s[48:49] offset:1536 sc1
	global_store_dword v247, v234, s[60:61] offset:768 sc1
	v_pk_mul_f32 v[18:19], v[18:19], v[208:209] op_sel_hi:[1,0]
	v_pk_mul_f32 v[20:21], v[20:21], v[208:209] op_sel_hi:[1,0]
	v_pk_fma_f32 v[18:19], v[18:19], v[222:223], v[226:227]
	v_pk_fma_f32 v[20:21], v[20:21], v[224:225], v[228:229]
	v_med3_f32 v238, v18, s33, v160
	v_med3_f32 v239, v19, s33, v160
	v_med3_f32 v240, v20, s33, v160
	v_med3_f32 v241, v21, s33, v160
	v_cvt_pk_fp8_f32 v242, v238, v239
	v_cvt_pk_bf16_f32 v244, v18, v19
	v_cvt_pk_bf16_f32 v245, v20, v21
	v_cvt_pk_fp8_f32 v242, v240, v241 op_sel:[0,0,1]
	global_store_dwordx2 v246, v[244:245], s[50:51] offset:1536 sc1
	global_store_dword v247, v242, s[62:63] offset:768 sc1
	ds_read_b128 v[222:225], v133 offset:5120
	ds_read_b128 v[226:229], v133 offset:13312
	s_waitcnt lgkmcnt(2)
; #define GAS __attribute__((address_space(1)))
; __device__ __forceinline__ unsigned pk2(float lo, float hi) { return pg8::cvt_pk_bf16(lo, hi); }
; __device__ __forceinline__ unsigned pk4f8(float a, float b, float c, float d) { int p = __builtin_amdgcn_cvt_pk_fp8_f32(sat8(a), sat8(b), 0, false); p = __builtin_amdgcn_cvt_pk_fp8_f32(sat8(c), sat8(d), p, true); return (unsigned)p; }
; template <bool WT = true> __device__ __forceinline__ void h_store_tab(const HRow& X, const LAS f32x4* GS, const LAS f32x4* SH, bf16* hrow, unsigned char* h8row, int lane, float* rms_slot) {
;     ...
; #pragma unroll
;     for (int j = 0; j < 8; ++j) { const f32x4 h = X.v[j] * rr * GS[lane + 64 * j] + SH[lane + 64 * j]; const unsigned w0 = pk2(h[0], h[1]), w1 = pk2(h[2], h[3]);
;         const unsigned w8 = pk4f8(h[0], h[1], h[2], h[3]);
;         if (WT) { __hip_atomic_store((unsigned long long*)(hrow) + lane + 64 * j, ((unsigned long long)w1 << 32) | w0, RLX_AGENT); __hip_atomic_store((unsigned*)h8row + lane + 64 * j, w8, RLX_AGENT); }
;         else { ((GAS v2u*)hrow)[lane + 64 * j] = (v2u){w0, w1}; ((unsigned*)h8row)[lane + 64 * j] = w8; } }
	v_pk_mul_f32 v[110:111], v[110:111], v[202:203] op_sel_hi:[1,0]
	v_pk_mul_f32 v[112:113], v[112:113], v[202:203] op_sel_hi:[1,0]
	v_pk_fma_f32 v[110:111], v[110:111], v[214:215], v[218:219]
	v_pk_fma_f32 v[112:113], v[112:113], v[216:217], v[220:221]
	v_med3_f32 v230, v110, s33, v160
	v_med3_f32 v231, v111, s33, v160
	v_med3_f32 v232, v112, s33, v160
	v_med3_f32 v233, v113, s33, v160
	v_cvt_pk_fp8_f32 v234, v230, v231
	v_cvt_pk_bf16_f32 v236, v110, v111
	v_cvt_pk_bf16_f32 v237, v112, v113
	v_cvt_pk_fp8_f32 v234, v232, v233 op_sel:[0,0,1]
	global_store_dwordx2 v246, v[236:237], s[44:45] offset:2048 sc1
	global_store_dword v247, v234, s[52:53] offset:1024 sc1
	v_pk_mul_f32 v[78:79], v[78:79], v[204:205] op_sel_hi:[1,0]
	v_pk_mul_f32 v[80:81], v[80:81], v[204:205] op_sel_hi:[1,0]
	v_pk_fma_f32 v[78:79], v[78:79], v[214:215], v[218:219]
	v_pk_fma_f32 v[80:81], v[80:81], v[216:217], v[220:221]
	v_med3_f32 v238, v78, s33, v160
	v_med3_f32 v239, v79, s33, v160
	v_med3_f32 v240, v80, s33, v160
	v_med3_f32 v241, v81, s33, v160
	v_cvt_pk_fp8_f32 v242, v238, v239
	v_cvt_pk_bf16_f32 v244, v78, v79
	v_cvt_pk_bf16_f32 v245, v80, v81
	v_cvt_pk_fp8_f32 v242, v240, v241 op_sel:[0,0,1]
	global_store_dwordx2 v246, v[244:245], s[46:47] offset:2048 sc1
	global_store_dword v247, v242, s[54:55] offset:1024 sc1
	v_pk_mul_f32 v[46:47], v[46:47], v[206:207] op_sel_hi:[1,0]
	v_pk_mul_f32 v[48:49], v[48:49], v[206:207] op_sel_hi:[1,0]
	v_pk_fma_f32 v[46:47], v[46:47], v[214:215], v[218:219]
	v_pk_fma_f32 v[48:49], v[48:49], v[216:217], v[220:221]
	v_med3_f32 v230, v46, s33, v160
	v_med3_f32 v231, v47, s33, v160
	v_med3_f32 v232, v48, s33, v160
	v_med3_f32 v233, v49, s33, v160
	v_cvt_pk_fp8_f32 v234, v230, v231
	v_cvt_pk_bf16_f32 v236, v46, v47
	v_cvt_pk_bf16_f32 v237, v48, v49
	v_cvt_pk_fp8_f32 v234, v232, v233 op_sel:[0,0,1]
	global_store_dwordx2 v246, v[236:237], s[48:49] offset:2048 sc1
	global_store_dword v247, v234, s[60:61] offset:1024 sc1
	v_pk_mul_f32 v[14:15], v[14:15], v[208:209] op_sel_hi:[1,0]
	v_pk_mul_f32 v[16:17], v[16:17], v[208:209] op_sel_hi:[1,0]
	v_pk_fma_f32 v[14:15], v[14:15], v[214:215], v[218:219]
	v_pk_fma_f32 v[16:17], v[16:17], v[216:217], v[220:221]
	v_med3_f32 v238, v14, s33, v160
	v_med3_f32 v239, v15, s33, v160
	v_med3_f32 v240, v16, s33, v160
	v_med3_f32 v241, v17, s33, v160
	v_cvt_pk_fp8_f32 v242, v238, v239
	v_cvt_pk_bf16_f32 v244, v14, v15
	v_cvt_pk_bf16_f32 v245, v16, v17
	v_cvt_pk_fp8_f32 v242, v240, v241 op_sel:[0,0,1]
	global_store_dwordx2 v246, v[244:245], s[50:51] offset:2048 sc1
	global_store_dword v247, v242, s[62:63] offset:1024 sc1
	ds_read_b128 v[214:217], v133 offset:6144
	ds_read_b128 v[218:221], v133 offset:14336
	s_waitcnt lgkmcnt(2)
	v_pk_mul_f32 v[106:107], v[106:107], v[202:203] op_sel_hi:[1,0]
	v_pk_mul_f32 v[108:109], v[108:109], v[202:203] op_sel_hi:[1,0]
	v_pk_fma_f32 v[106:107], v[106:107], v[222:223], v[226:227]
	v_pk_fma_f32 v[108:109], v[108:109], v[224:225], v[228:229]
	v_med3_f32 v230, v106, s33, v160
	v_med3_f32 v231, v107, s33, v160
	v_med3_f32 v232, v108, s33, v160
	v_med3_f32 v233, v109, s33, v160
	v_cvt_pk_fp8_f32 v234, v230, v231
	v_cvt_pk_bf16_f32 v236, v106, v107
	v_cvt_pk_bf16_f32 v237, v108, v109
	v_cvt_pk_fp8_f32 v234, v232, v233 op_sel:[0,0,1]
	global_store_dwordx2 v246, v[236:237], s[44:45] offset:2560 sc1
	global_store_dword v247, v234, s[52:53] offset:1280 sc1
	v_pk_mul_f32 v[74:75], v[74:75], v[204:205] op_sel_hi:[1,0]
	v_pk_mul_f32 v[76:77], v[76:77], v[204:205] op_sel_hi:[1,0]
	v_pk_fma_f32 v[74:75], v[74:75], v[222:223], v[226:227]
	v_pk_fma_f32 v[76:77], v[76:77], v[224:225], v[228:229]
	v_med3_f32 v238, v74, s33, v160
	v_med3_f32 v239, v75, s33, v160
	v_med3_f32 v240, v76, s33, v160
	v_med3_f32 v241, v77, s33, v160
	v_cvt_pk_fp8_f32 v242, v238, v239
	v_cvt_pk_bf16_f32 v244, v74, v75
	v_cvt_pk_bf16_f32 v245, v76, v77
	v_cvt_pk_fp8_f32 v242, v240, v241 op_sel:[0,0,1]
	global_store_dwordx2 v246, v[244:245], s[46:47] offset:2560 sc1
	global_store_dword v247, v242, s[54:55] offset:1280 sc1
	v_pk_mul_f32 v[42:43], v[42:43], v[206:207] op_sel_hi:[1,0]
	v_pk_mul_f32 v[44:45], v[44:45], v[206:207] op_sel_hi:[1,0]
	v_pk_fma_f32 v[42:43], v[42:43], v[222:223], v[226:227]
	v_pk_fma_f32 v[44:45], v[44:45], v[224:225], v[228:229]
	v_med3_f32 v230, v42, s33, v160
	v_med3_f32 v231, v43, s33, v160
	v_med3_f32 v232, v44, s33, v160
	v_med3_f32 v233, v45, s33, v160
	v_cvt_pk_fp8_f32 v234, v230, v231
	v_cvt_pk_bf16_f32 v236, v42, v43
	v_cvt_pk_bf16_f32 v237, v44, v45
	v_cvt_pk_fp8_f32 v234, v232, v233 op_sel:[0,0,1]
	global_store_dwordx2 v246, v[236:237], s[48:49] offset:2560 sc1
	global_store_dword v247, v234, s[60:61] offset:1280 sc1
	v_pk_mul_f32 v[10:11], v[10:11], v[208:209] op_sel_hi:[1,0]
	v_pk_mul_f32 v[12:13], v[12:13], v[208:209] op_sel_hi:[1,0]
	v_pk_fma_f32 v[10:11], v[10:11], v[222:223], v[226:227]
	v_pk_fma_f32 v[12:13], v[12:13], v[224:225], v[228:229]
	v_med3_f32 v238, v10, s33, v160
	v_med3_f32 v239, v11, s33, v160
	v_med3_f32 v240, v12, s33, v160
	v_med3_f32 v241, v13, s33, v160
	v_cvt_pk_fp8_f32 v242, v238, v239
	v_cvt_pk_bf16_f32 v244, v10, v11
	v_cvt_pk_bf16_f32 v245, v12, v13
	v_cvt_pk_fp8_f32 v242, v240, v241 op_sel:[0,0,1]
	global_store_dwordx2 v246, v[244:245], s[50:51] offset:2560 sc1
	global_store_dword v247, v242, s[62:63] offset:1280 sc1
	ds_read_b128 v[222:225], v133 offset:7168
	ds_read_b128 v[226:229], v133 offset:15360
	s_waitcnt lgkmcnt(2)
; #define GAS __attribute__((address_space(1)))
; __device__ __forceinline__ unsigned pk2(float lo, float hi) { return pg8::cvt_pk_bf16(lo, hi); }
; __device__ __forceinline__ unsigned pk4f8(float a, float b, float c, float d) { int p = __builtin_amdgcn_cvt_pk_fp8_f32(sat8(a), sat8(b), 0, false); p = __builtin_amdgcn_cvt_pk_fp8_f32(sat8(c), sat8(d), p, true); return (unsigned)p; }
; template <bool WT = true> __device__ __forceinline__ void h_store_tab(const HRow& X, const LAS f32x4* GS, const LAS f32x4* SH, bf16* hrow, unsigned char* h8row, int lane, float* rms_slot) {
;     ...
; #pragma unroll
;     for (int j = 0; j < 8; ++j) { const f32x4 h = X.v[j] * rr * GS[lane + 64 * j] + SH[lane + 64 * j]; const unsigned w0 = pk2(h[0], h[1]), w1 = pk2(h[2], h[3]);
;         const unsigned w8 = pk4f8(h[0], h[1], h[2], h[3]);
;         if (WT) { __hip_atomic_store((unsigned long long*)(hrow) + lane + 64 * j, ((unsigned long long)w1 << 32) | w0, RLX_AGENT); __hip_atomic_store((unsigned*)h8row + lane + 64 * j, w8, RLX_AGENT); }
;         else { ((GAS v2u*)hrow)[lane + 64 * j] = (v2u){w0, w1}; ((unsigned*)h8row)[lane + 64 * j] = w8; } }
; __device__ __forceinline__ void p2_from_regs(const Args& a, const Ctx& C, const HRow& x0, const HRow& x1, const HRow& x2, const HRow& x3) {
;     ...
;     asm volatile("s_waitcnt vmcnt(0)" ::: "memory"); __syncthreads();
;     if (C.tid == 0) __hip_atomic_fetch_add(g_ctl + CW_HRDY + 64 * (j >> 3), 1u, RLX_AGENT);
	v_pk_mul_f32 v[102:103], v[102:103], v[202:203] op_sel_hi:[1,0]
	v_pk_mul_f32 v[104:105], v[104:105], v[202:203] op_sel_hi:[1,0]
	v_pk_fma_f32 v[102:103], v[102:103], v[214:215], v[218:219]
	v_pk_fma_f32 v[104:105], v[104:105], v[216:217], v[220:221]
	v_med3_f32 v230, v102, s33, v160
	v_med3_f32 v231, v103, s33, v160
	v_med3_f32 v232, v104, s33, v160
	v_med3_f32 v233, v105, s33, v160
	v_cvt_pk_fp8_f32 v234, v230, v231
	v_cvt_pk_bf16_f32 v236, v102, v103
	v_cvt_pk_bf16_f32 v237, v104, v105
	v_cvt_pk_fp8_f32 v234, v232, v233 op_sel:[0,0,1]
	global_store_dwordx2 v246, v[236:237], s[44:45] offset:3072 sc1
	global_store_dword v247, v234, s[52:53] offset:1536 sc1
	v_pk_mul_f32 v[70:71], v[70:71], v[204:205] op_sel_hi:[1,0]
	v_pk_mul_f32 v[72:73], v[72:73], v[204:205] op_sel_hi:[1,0]
	v_pk_fma_f32 v[70:71], v[70:71], v[214:215], v[218:219]
	v_pk_fma_f32 v[72:73], v[72:73], v[216:217], v[220:221]
	v_med3_f32 v238, v70, s33, v160
	v_med3_f32 v239, v71, s33, v160
	v_med3_f32 v240, v72, s33, v160
	v_med3_f32 v241, v73, s33, v160
	v_cvt_pk_fp8_f32 v242, v238, v239
	v_cvt_pk_bf16_f32 v244, v70, v71
	v_cvt_pk_bf16_f32 v245, v72, v73
	v_cvt_pk_fp8_f32 v242, v240, v241 op_sel:[0,0,1]
	global_store_dwordx2 v246, v[244:245], s[46:47] offset:3072 sc1
	global_store_dword v247, v242, s[54:55] offset:1536 sc1
	v_pk_mul_f32 v[38:39], v[38:39], v[206:207] op_sel_hi:[1,0]
	v_pk_mul_f32 v[40:41], v[40:41], v[206:207] op_sel_hi:[1,0]
	v_pk_fma_f32 v[38:39], v[38:39], v[214:215], v[218:219]
	v_pk_fma_f32 v[40:41], v[40:41], v[216:217], v[220:221]
	v_med3_f32 v230, v38, s33, v160
	v_med3_f32 v231, v39, s33, v160
	v_med3_f32 v232, v40, s33, v160
	v_med3_f32 v233, v41, s33, v160
	v_cvt_pk_fp8_f32 v234, v230, v231
	v_cvt_pk_bf16_f32 v236, v38, v39
	v_cvt_pk_bf16_f32 v237, v40, v41
	v_cvt_pk_fp8_f32 v234, v232, v233 op_sel:[0,0,1]
	global_store_dwordx2 v246, v[236:237], s[48:49] offset:3072 sc1
	global_store_dword v247, v234, s[60:61] offset:1536 sc1
	v_pk_mul_f32 v[6:7], v[6:7], v[208:209] op_sel_hi:[1,0]
	v_pk_mul_f32 v[8:9], v[8:9], v[208:209] op_sel_hi:[1,0]
	v_pk_fma_f32 v[6:7], v[6:7], v[214:215], v[218:219]
	v_pk_fma_f32 v[8:9], v[8:9], v[216:217], v[220:221]
	v_med3_f32 v238, v6, s33, v160
	v_med3_f32 v239, v7, s33, v160
	v_med3_f32 v240, v8, s33, v160
	v_med3_f32 v241, v9, s33, v160
	v_cvt_pk_fp8_f32 v242, v238, v239
	v_cvt_pk_bf16_f32 v244, v6, v7
	v_cvt_pk_bf16_f32 v245, v8, v9
	v_cvt_pk_fp8_f32 v242, v240, v241 op_sel:[0,0,1]
	global_store_dwordx2 v246, v[244:245], s[50:51] offset:3072 sc1
	global_store_dword v247, v242, s[62:63] offset:1536 sc1
	s_waitcnt lgkmcnt(0)
	v_pk_mul_f32 v[98:99], v[98:99], v[202:203] op_sel_hi:[1,0]
	v_pk_mul_f32 v[100:101], v[100:101], v[202:203] op_sel_hi:[1,0]
	v_pk_fma_f32 v[98:99], v[98:99], v[222:223], v[226:227]
	v_pk_fma_f32 v[100:101], v[100:101], v[224:225], v[228:229]
	v_med3_f32 v230, v98, s33, v160
	v_med3_f32 v231, v99, s33, v160
	v_med3_f32 v232, v100, s33, v160
	v_med3_f32 v233, v101, s33, v160
	v_cvt_pk_fp8_f32 v234, v230, v231
	v_cvt_pk_bf16_f32 v236, v98, v99
	v_cvt_pk_bf16_f32 v237, v100, v101
	v_cvt_pk_fp8_f32 v234, v232, v233 op_sel:[0,0,1]
	global_store_dwordx2 v246, v[236:237], s[44:45] offset:3584 sc1
	global_store_dword v247, v234, s[52:53] offset:1792 sc1
	v_pk_mul_f32 v[66:67], v[66:67], v[204:205] op_sel_hi:[1,0]
	v_pk_mul_f32 v[68:69], v[68:69], v[204:205] op_sel_hi:[1,0]
	v_pk_fma_f32 v[66:67], v[66:67], v[222:223], v[226:227]
	v_pk_fma_f32 v[68:69], v[68:69], v[224:225], v[228:229]
	v_med3_f32 v238, v66, s33, v160
	v_med3_f32 v239, v67, s33, v160
	v_med3_f32 v240, v68, s33, v160
	v_med3_f32 v241, v69, s33, v160
	v_cvt_pk_fp8_f32 v242, v238, v239
	v_cvt_pk_bf16_f32 v244, v66, v67
	v_cvt_pk_bf16_f32 v245, v68, v69
	v_cvt_pk_fp8_f32 v242, v240, v241 op_sel:[0,0,1]
	global_store_dwordx2 v246, v[244:245], s[46:47] offset:3584 sc1
	global_store_dword v247, v242, s[54:55] offset:1792 sc1
	v_pk_mul_f32 v[34:35], v[34:35], v[206:207] op_sel_hi:[1,0]
	v_pk_mul_f32 v[36:37], v[36:37], v[206:207] op_sel_hi:[1,0]
	v_pk_fma_f32 v[34:35], v[34:35], v[222:223], v[226:227]
	v_pk_fma_f32 v[36:37], v[36:37], v[224:225], v[228:229]
	v_med3_f32 v230, v34, s33, v160
	v_med3_f32 v231, v35, s33, v160
	v_med3_f32 v232, v36, s33, v160
	v_med3_f32 v233, v37, s33, v160
	v_cvt_pk_fp8_f32 v234, v230, v231
	v_cvt_pk_bf16_f32 v236, v34, v35
	v_cvt_pk_bf16_f32 v237, v36, v37
	v_cvt_pk_fp8_f32 v234, v232, v233 op_sel:[0,0,1]
	global_store_dwordx2 v246, v[236:237], s[48:49] offset:3584 sc1
	global_store_dword v247, v234, s[60:61] offset:1792 sc1
	v_pk_mul_f32 v[2:3], v[2:3], v[208:209] op_sel_hi:[1,0]
	v_pk_mul_f32 v[4:5], v[4:5], v[208:209] op_sel_hi:[1,0]
	v_pk_fma_f32 v[2:3], v[2:3], v[222:223], v[226:227]
	v_pk_fma_f32 v[4:5], v[4:5], v[224:225], v[228:229]
	v_med3_f32 v238, v2, s33, v160
	v_med3_f32 v239, v3, s33, v160
	v_med3_f32 v240, v4, s33, v160
	v_med3_f32 v241, v5, s33, v160
	v_cvt_pk_fp8_f32 v242, v238, v239
	v_cvt_pk_bf16_f32 v244, v2, v3
	v_cvt_pk_bf16_f32 v245, v4, v5
	v_cvt_pk_fp8_f32 v242, v240, v241 op_sel:[0,0,1]
	global_store_dwordx2 v246, v[244:245], s[50:51] offset:3584 sc1
	global_store_dword v247, v242, s[62:63] offset:1792 sc1
	s_mov_b32 s9, 0
	s_waitcnt vmcnt(0)
	s_waitcnt vmcnt(63) expcnt(7) lgkmcnt(15)
	s_barrier
	s_mov_b64 s[4:5], exec
	v_readlane_b32 s6, v249, 17
	v_readlane_b32 s7, v249, 18
	s_and_b64 s[6:7], s[4:5], s[6:7]
	s_mov_b64 exec, s[6:7]
	s_cbranch_execz .LBB0_308
	s_mov_b64 s[6:7], exec
	v_mbcnt_lo_u32_b32 v2, s6, 0
	v_mbcnt_hi_u32_b32 v2, s7, v2
	v_cmp_eq_u32_e32 vcc, 0, v2
	s_and_b64 s[10:11], exec, vcc
	s_mov_b64 exec, s[10:11]
	s_cbranch_execz .LBB0_308
	s_lshl_b32 s0, s0, 3
	s_and_b32 s8, s0, 0xffffffc0
	s_lshl_b64 s[0:1], s[8:9], 2
	s_getpc_b64 s[8:9]
	s_add_u32 s8, s8, g_ctl@rel32@lo+40964
	s_addc_u32 s9, s9, g_ctl@rel32@hi+40972
	s_add_u32 s0, s8, s0
	s_addc_u32 s1, s9, s1
	s_bcnt1_i32_b64 s2, s[6:7]
	v_mov_b32_e32 v2, 0
	v_mov_b32_e32 v3, s2
	global_atomic_add v2, v3, s[0:1]

; __device__ __forceinline__ float ld_agent_f32(const float* p) { return __uint_as_float(__hip_atomic_load((const unsigned*)p, RLX_AGENT)); }
; __device__ __forceinline__ void gmlp_load(GmlpRegs& R, const Args& a, const Ctx& C, int c, int hd) {
;     const bf16* PROJ = (const bf16*)(a.ws + WS_PROJ); const float* VST = (const float*)(a.ws + WS_CTL) + CW_VSTAT;
;     const int lane = C.lane, fr = lane & 15, q = lane >> 4, w = C.wave, tid = C.tid;
;     const size_t T0 = (size_t)c * 128; const int ch = hd * 128 + 16 * w + fr, chs = hd * 128 + 16 * w + 4 * q;
;     const float* W = a.in[I_WS] + (size_t)hd * 128 * 128;
; #pragma unroll
;     for (int i = 0; i < 8; ++i) R.wv[i] = ((const f32x4*)W)[tid + 512 * i];
; #pragma unroll
;     for (int i = 0; i < 4; ++i) { const int idx = tid + 512 * i; R.vv[i] = *(const v4u*)(PROJ + (T0 + (idx >> 4)) * DIN + DA + hd * 128 + (idx & 15) * 8); }
;     R.s1 = 0.f; R.s2 = 0.f;
;     if (tid < 128) { R.s1 = ld_agent_f32(VST + 2 * (T0 + tid)); R.s2 = ld_agent_f32(VST + 2 * (T0 + tid) + 1); }
;     R.lg = a.in[I_LNG][ch]; R.lb = a.in[I_LNB][ch];
; #pragma unroll
;     for (int nt = 0; nt < 8; ++nt) { const size_t row = T0 + 16 * nt + fr; R.uq[nt] = *(const v2u*)(PROJ + row * DIN + chs); R.bsv[nt] = a.in[I_BS][hd * 128 + 16 * nt + fr]; }
.LBB0_964:
	v_readlane_b32 s0, v249, 19
	v_readlane_b32 s1, v249, 20
	s_andn2_b64 vcc, exec, s[0:1]
	s_cbranch_vccnz .LBB0_989
	v_readlane_b32 s0, v249, 0
	s_ashr_i32 s10, s0, 3
	s_and_b32 s0, s0, 7
	s_ashr_i32 s11, s10, 31
	s_lshl_b32 s1, s0, 7
	s_lshl_b32 s2, s0, 16
	s_add_u32 s14, s20, s2
	v_mov_b32_e32 v113, 0
	s_addc_u32 s15, s21, 0
	v_lshlrev_b32_e32 v94, 4, v0
	v_mov_b32_e32 v95, v113
	s_waitcnt lgkmcnt(1)
	v_lshl_add_u64 v[2:3], s[14:15], 0, v[94:95]
	s_movk_i32 s2, 0x2000
	v_add_co_u32_e32 v4, vcc, s2, v2
	v_or_b32_e32 v147, 0x400, v0
	s_waitcnt lgkmcnt(0)
	v_addc_co_u32_e32 v5, vcc, 0, v3, vcc
	s_movk_i32 s2, 0x6000
	global_load_dwordx4 v[26:29], v94, s[14:15]
	v_lshlrev_b32_e32 v148, 4, v147
	global_load_dwordx4 v[30:33], v[4:5], off
	global_load_dwordx4 v[18:21], v148, s[14:15]
	v_add_co_u32_e32 v4, vcc, s2, v2
	s_mov_b32 s2, 0x8000
	s_nop 0
	v_addc_co_u32_e32 v5, vcc, 0, v3, vcc
	v_add_co_u32_e32 v6, vcc, s2, v2
	s_mov_b32 s2, 0xa000
	s_nop 0
	v_addc_co_u32_e32 v7, vcc, 0, v3, vcc
	v_or_b32_e32 v146, 0x200, v0
	global_load_dwordx4 v[22:25], v[4:5], off
	global_load_dwordx4 v[10:13], v[6:7], off
	v_add_co_u32_e32 v4, vcc, s2, v2
	s_lshl_b64 s[10:11], s[10:11], 7
	v_lshlrev_b32_e32 v70, 3, v0
	v_lshrrev_b32_e32 v71, 4, v0
	v_addc_co_u32_e32 v5, vcc, 0, v3, vcc
	s_mov_b32 s2, 0xc000
	v_and_b32_e32 v38, 0x78, v70
	v_or_b32_e32 v36, s10, v71
	s_movk_i32 s20, 0x2800
	v_mov_b64_e32 v[34:35], s[6:7]
	v_lshrrev_b32_e32 v72, 4, v146
	v_add_co_u32_e32 v6, vcc, s2, v2
	v_mad_u64_u32 v[36:37], s[14:15], v36, s20, v[34:35]
	v_mov_b32_e32 v42, 0x2800
	v_lshlrev_b32_e32 v112, 1, v38
	v_or_b32_e32 v38, s10, v72
	s_mov_b32 s9, 0
	v_addc_co_u32_e32 v7, vcc, 0, v3, vcc
	s_mov_b32 s2, 0xe000
	v_mad_i32_i24 v37, s11, v42, v37
	s_lshl_b32 s8, s0, 8
	v_mad_u64_u32 v[38:39], s[14:15], v38, s20, v[34:35]
	v_add_co_u32_e32 v2, vcc, s2, v2
	v_lshl_add_u64 v[36:37], v[36:37], 0, s[8:9]
	v_mad_i32_i24 v39, s11, v42, v39
	v_or_b32_e32 v95, 0x600, v0
	v_addc_co_u32_e32 v3, vcc, 0, v3, vcc
	v_lshl_add_u64 v[36:37], v[36:37], 0, v[112:113]
	v_lshl_add_u64 v[38:39], v[38:39], 0, s[8:9]
	v_lshrrev_b32_e32 v73, 4, v147
	global_load_dwordx4 v[14:17], v[4:5], off
	s_nop 0
	global_load_dwordx4 v[6:9], v[6:7], off
	v_lshl_add_u64 v[38:39], v[38:39], 0, v[112:113]
	global_load_dwordx4 v[2:5], v[2:3], off
	s_nop 0
	global_load_dwordx4 v[54:57], v[36:37], off offset:2048
	global_load_dwordx4 v[50:53], v[38:39], off offset:2048
	v_or_b32_e32 v36, s10, v73
	v_lshrrev_b32_e32 v74, 4, v95
	v_mad_u64_u32 v[36:37], s[14:15], v36, s20, v[34:35]
	v_or_b32_e32 v38, s10, v74
	v_mad_i32_i24 v37, s11, v42, v37
	v_mad_u64_u32 v[34:35], s[14:15], v38, s20, v[34:35]
	v_lshl_add_u64 v[36:37], v[36:37], 0, s[8:9]
	v_mad_i32_i24 v35, s11, v42, v35
	v_lshl_add_u64 v[36:37], v[36:37], 0, v[112:113]
	v_lshl_add_u64 v[34:35], v[34:35], 0, s[8:9]
	v_lshl_add_u64 v[34:35], v[34:35], 0, v[112:113]
	global_load_dwordx4 v[62:65], v[36:37], off offset:2048
	global_load_dwordx4 v[58:61], v[34:35], off offset:2048
	s_movk_i32 s0, 0x80
	v_cmp_gt_u32_e32 vcc, s0, v0
	v_mov_b32_e32 v66, v113
	v_mov_b32_e32 v67, v113
	s_and_saveexec_b64 s[14:15], vcc
	s_cbranch_execz .LBB0_967
	v_mov_b32_e32 v35, s11
	v_or_b32_e32 v34, s10, v0
	v_lshl_add_u64 v[34:35], v[34:35], 3, s[4:5]
	global_load_dword v251, v[34:35], off sc1
	global_load_dword v250, v[34:35], off offset:4 sc1
	s_mov_b32 s0, 0x3a800000
.LBB0_967:
	s_or_b64 exec, exec, s[14:15]
	v_readlane_b32 s0, v249, 0
	s_lshl_b32 s2, s82, 4
	s_add_i32 s8, s0, 0x100
	s_add_i32 s0, s1, s2
	v_lshrrev_b32_e32 v34, 2, v0
	v_and_b32_e32 v149, 15, v0
	v_and_or_b32 v38, v34, 12, s0
	v_or_b32_e32 v34, s0, v149
	v_mov_b32_e32 v35, v113
	v_lshlrev_b64 v[34:35], 2, v[34:35]
	v_lshl_add_u64 v[36:37], s[16:17], 0, v[34:35]
	v_lshl_add_u64 v[34:35], s[18:19], 0, v[34:35]
	global_load_dword v100, v[34:35], off
	v_lshlrev_b32_e32 v34, 1, v38
	v_mov_b32_e32 v35, v113
	global_load_dword v98, v[36:37], off
	v_lshl_add_u64 v[68:69], s[6:7], 0, v[34:35]
	v_or_b32_e32 v36, s1, v149
	v_or_b32_e32 v136, s10, v149
	v_or_b32_e32 v75, 16, v149
	v_or_b32_e32 v76, 32, v149
	v_or_b32_e32 v77, 48, v149
	v_mad_u64_u32 v[34:35], s[14:15], v136, s20, v[68:69]
	v_lshlrev_b32_e32 v43, 2, v36
	v_or_b32_e32 v36, s10, v75
	v_or_b32_e32 v38, s10, v76
	v_or_b32_e32 v40, s10, v77
	v_mad_i32_i24 v35, s11, v42, v35
	v_mad_u64_u32 v[36:37], s[14:15], v36, s20, v[68:69]
	v_mad_u64_u32 v[38:39], s[14:15], v38, s20, v[68:69]
	v_mad_u64_u32 v[40:41], s[14:15], v40, s20, v[68:69]
	v_or_b32_e32 v78, 64, v149
	v_mad_i32_i24 v37, s11, v42, v37
	v_mad_i32_i24 v39, s11, v42, v39
	v_mad_i32_i24 v41, s11, v42, v41
	global_load_dwordx2 v[140:141], v[34:35], off
	global_load_dwordx2 v[138:139], v[36:37], off
	global_load_dwordx2 v[134:135], v[38:39], off
	global_load_dwordx2 v[132:133], v[40:41], off
	v_or_b32_e32 v34, s10, v78
	v_or_b32_e32 v79, 0x50, v149
	v_or_b32_e32 v80, 0x60, v149
	v_or_b32_e32 v81, 0x70, v149
	v_mad_u64_u32 v[34:35], s[14:15], v34, s20, v[68:69]
	v_or_b32_e32 v36, s10, v79
	v_or_b32_e32 v38, s10, v80
	v_or_b32_e32 v40, s10, v81
	v_mad_i32_i24 v35, s11, v42, v35
	v_mad_u64_u32 v[36:37], s[14:15], v36, s20, v[68:69]
	v_mad_u64_u32 v[38:39], s[14:15], v38, s20, v[68:69]
	v_mad_u64_u32 v[40:41], s[14:15], v40, s20, v[68:69]
	v_mad_i32_i24 v37, s11, v42, v37
	v_mad_i32_i24 v39, s11, v42, v39
	v_mad_i32_i24 v41, s11, v42, v41
	global_load_dwordx2 v[130:131], v[34:35], off
	global_load_dwordx2 v[126:127], v[36:37], off
	global_load_dwordx2 v[124:125], v[38:39], off
	global_load_dwordx2 v[122:123], v[40:41], off
	global_load_dword v161, v43, s[22:23]
	global_load_dword v160, v43, s[22:23] offset:64
; #define LAS __attribute__((address_space(3)))
; #define PIN(x) asm volatile("" : "+v"(x))
; __device__ __forceinline__ unsigned pk2(float lo, float hi) { return pg8::cvt_pk_bf16(lo, hi); }
; __device__ __forceinline__ float ld_agent_f32(const float* p) { return __uint_as_float(__hip_atomic_load((const unsigned*)p, RLX_AGENT)); }
; __device__ __forceinline__ void gmlp_load(GmlpRegs& R, const Args& a, const Ctx& C, int c, int hd) {
;     ...
;     for (int i = 0; i < 8; ++i) R.wv[i] = ((const f32x4*)W)[tid + 512 * i];
; #pragma unroll
;     for (int i = 0; i < 4; ++i) { const int idx = tid + 512 * i; R.vv[i] = *(const v4u*)(PROJ + (T0 + (idx >> 4)) * DIN + DA + hd * 128 + (idx & 15) * 8); }
;     R.s1 = 0.f; R.s2 = 0.f;
;     if (tid < 128) { R.s1 = ld_agent_f32(VST + 2 * (T0 + tid)); R.s2 = ld_agent_f32(VST + 2 * (T0 + tid) + 1); }
;     R.lg = a.in[I_LNG][ch]; R.lb = a.in[I_LNB][ch];
; #pragma unroll
;     for (int nt = 0; nt < 8; ++nt) { const size_t row = T0 + 16 * nt + fr; R.uq[nt] = *(const v2u*)(PROJ + row * DIN + chs); R.bsv[nt] = a.in[I_BS][hd * 128 + 16 * nt + fr]; }
; __device__ __forceinline__ void gmlp_compute(GmlpRegs& R, const Args& a, const Ctx& C, int c, int hd) {
;     ...
;     for (int i = 0; i < 8; ++i) PIN(R.wv[i]);
; #pragma unroll
;     for (int i = 0; i < 4; ++i) PIN(R.vv[i]);
;     __syncthreads();
; #pragma unroll
;     for (int i = 0; i < 8; ++i) { const int idx = tid + 512 * i, tr = idx >> 5, c4 = (idx & 31) * 4; f32x4 x = R.wv[i];
; #pragma unroll
;         for (int j = 0; j < 4; ++j) x[j] = (c4 + j <= tr) ? x[j] : 0.f;
;         *(LAS v2u*)(WL + tr * 272 + c4 * 2) = (v2u){pk2(x[0], x[1]), pk2(x[2], x[3])}; }
	global_load_dword v159, v43, s[22:23] offset:128
	global_load_dword v156, v43, s[22:23] offset:192
	global_load_dword v154, v43, s[22:23] offset:256
	global_load_dword v152, v43, s[22:23] offset:320
	global_load_dword v151, v43, s[22:23] offset:384
	global_load_dword v150, v43, s[22:23] offset:448
	s_ashr_i32 s14, s8, 3
	s_ashr_i32 s15, s14, 31
	s_lshl_b64 s[14:15], s[14:15], 7
	v_or_b32_e32 v34, s14, v71
	v_mov_b64_e32 v[44:45], s[6:7]
	v_or_b32_e32 v36, s14, v72
	v_or_b32_e32 v43, s14, v73
	v_mad_u64_u32 v[34:35], s[6:7], v34, s20, v[44:45]
	v_mad_u64_u32 v[36:37], s[6:7], v36, s20, v[44:45]
	v_mad_u64_u32 v[46:47], s[6:7], v43, s20, v[44:45]
	v_or_b32_e32 v43, s14, v74
	v_mad_i32_i24 v35, s15, v42, v35
	s_lshl_b32 s8, s1, 1
	v_mad_i32_i24 v37, s15, v42, v37
	v_mad_i32_i24 v47, s15, v42, v47
	v_mad_u64_u32 v[44:45], s[6:7], v43, s20, v[44:45]
	v_lshl_add_u64 v[34:35], v[34:35], 0, s[8:9]
	v_lshl_add_u64 v[36:37], v[36:37], 0, s[8:9]
	v_lshl_add_u64 v[46:47], v[46:47], 0, s[8:9]
	v_mad_i32_i24 v45, s15, v42, v45
	v_lshl_add_u64 v[34:35], v[34:35], 0, v[112:113]
	v_lshl_add_u64 v[36:37], v[36:37], 0, v[112:113]
	v_lshl_add_u64 v[82:83], v[46:47], 0, v[112:113]
	v_lshl_add_u64 v[42:43], v[44:45], 0, s[8:9]
	global_load_dwordx4 v[38:41], v[34:35], off offset:2048
	s_nop 0
	global_load_dwordx4 v[34:37], v[36:37], off offset:2048
	v_lshl_add_u64 v[84:85], v[42:43], 0, v[112:113]
	global_load_dwordx4 v[46:49], v[82:83], off offset:2048
	global_load_dwordx4 v[42:45], v[84:85], off offset:2048
	v_mov_b32_e32 v137, s11
	v_mov_b32_e32 v121, 0
	s_and_saveexec_b64 s[6:7], vcc
	s_cbranch_execz .LBB0_969
	v_mov_b32_e32 v83, s15
	v_or_b32_e32 v82, s14, v0
	v_lshl_add_u64 v[82:83], v[82:83], 3, s[4:5]
	global_load_dword v253, v[82:83], off sc1
	global_load_dword v252, v[82:83], off offset:4 sc1
	s_mov_b32 s4, 0x3a800000
.LBB0_969:
	s_or_b64 exec, exec, s[6:7]
	s_movk_i32 s1, 0x2800
	v_or_b32_e32 v75, s14, v75
	v_mad_u64_u32 v[84:85], s[4:5], v75, s1, v[68:69]
	v_or_b32_e32 v75, s14, v76
	v_or_b32_e32 v116, s14, v149
	v_mad_u64_u32 v[86:87], s[4:5], v75, s1, v[68:69]
	v_or_b32_e32 v75, s14, v77
	v_mad_u64_u32 v[82:83], s[4:5], v116, s1, v[68:69]
	v_mov_b32_e32 v88, 0x2800
	v_mad_u64_u32 v[76:77], s[4:5], v75, s1, v[68:69]
	v_mad_i32_i24 v83, s15, v88, v83
	v_mad_i32_i24 v77, s15, v88, v77
	v_or_b32_e32 v75, s14, v78
	v_mad_i32_i24 v85, s15, v88, v85
	v_mad_i32_i24 v87, s15, v88, v87
	global_load_dwordx2 v[110:111], v[82:83], off
	global_load_dwordx2 v[118:119], v[84:85], off
	global_load_dwordx2 v[114:115], v[86:87], off
	global_load_dwordx2 v[108:109], v[76:77], off
	v_mad_u64_u32 v[76:77], s[4:5], v75, s1, v[68:69]
	v_or_b32_e32 v75, s14, v79
	v_mad_u64_u32 v[78:79], s[4:5], v75, s1, v[68:69]
	v_or_b32_e32 v75, s14, v80
	v_mad_u64_u32 v[82:83], s[4:5], v75, s1, v[68:69]
	v_or_b32_e32 v75, s14, v81
	v_mad_i32_i24 v77, s15, v88, v77
	v_mad_u64_u32 v[68:69], s[4:5], v75, s1, v[68:69]
	v_mad_i32_i24 v79, s15, v88, v79
	v_mad_i32_i24 v83, s15, v88, v83
	v_mad_i32_i24 v69, s15, v88, v69
	global_load_dwordx2 v[106:107], v[76:77], off
	global_load_dwordx2 v[104:105], v[78:79], off
	global_load_dwordx2 v[102:103], v[82:83], off
	global_load_dwordx2 v[96:97], v[68:69], off
	s_waitcnt vmcnt(41)
	v_mov_b64_e32 v[78:79], v[28:29]
	v_mov_b64_e32 v[76:77], v[26:27]
	v_and_b32_e32 v75, 0x7c, v1
	v_lshrrev_b32_e32 v92, 5, v0
	v_cmp_gt_u32_e64 s[68:69], v75, v92
	v_cmp_lt_u32_e64 s[4:5], v75, v92
	s_waitcnt vmcnt(40)
	v_mov_b64_e32 v[82:83], v[32:33]
	v_cndmask_b32_e64 v68, v76, 0, s[68:69]
	v_or_b32_e32 v76, 2, v75
	v_cmp_gt_u32_e64 s[6:7], v76, v92
	v_cndmask_b32_e64 v69, 0, v77, s[4:5]
	s_waitcnt vmcnt(39)
	v_mov_b64_e32 v[86:87], v[20:21]
	v_cndmask_b32_e64 v77, v78, 0, s[6:7]
	v_or_b32_e32 v78, 3, v75
	v_cmp_gt_u32_e64 s[8:9], v78, v92
	s_waitcnt vmcnt(38)
	v_mov_b64_e32 v[90:91], v[24:25]
	s_waitcnt vmcnt(37)
	v_mov_b64_e32 v[144:145], v[12:13]
	s_waitcnt vmcnt(36)
	v_mov_b64_e32 v[176:177], v[16:17]
	s_waitcnt vmcnt(35)
	v_mov_b64_e32 v[180:181], v[8:9]
	s_waitcnt vmcnt(34)
	v_mov_b64_e32 v[184:185], v[4:5]
	v_lshl_add_u32 v164, v75, 1, 0
	v_cndmask_b32_e64 v79, v79, 0, s[8:9]
	s_movk_i32 s1, 0x110
	v_mov_b64_e32 v[80:81], v[30:31]
	v_mov_b64_e32 v[84:85], v[18:19]
	v_mov_b64_e32 v[88:89], v[22:23]
	v_mov_b64_e32 v[142:143], v[10:11]
	v_mov_b64_e32 v[174:175], v[14:15]
	v_mov_b64_e32 v[178:179], v[6:7]
	v_mov_b64_e32 v[182:183], v[2:3]
	v_cvt_pk_bf16_f32 v68, v68, v69
	v_cvt_pk_bf16_f32 v69, v77, v79
	v_mad_u32_u24 v77, v92, s1, v164
	s_waitcnt vmcnt(33)
	s_waitcnt vmcnt(32)
	s_waitcnt vmcnt(31)
	s_waitcnt vmcnt(30)
	s_barrier
; #define LAS __attribute__((address_space(3)))
; __device__ __forceinline__ unsigned pk2(float lo, float hi) { return pg8::cvt_pk_bf16(lo, hi); }
; __device__ __forceinline__ void gmlp_compute(GmlpRegs& R, const Args& a, const Ctx& C, int c, int hd) {
;     ...
;     __syncthreads();
; #pragma unroll
;     for (int i = 0; i < 8; ++i) { const int idx = tid + 512 * i, tr = idx >> 5, c4 = (idx & 31) * 4; f32x4 x = R.wv[i];
; #pragma unroll
;         for (int j = 0; j < 4; ++j) x[j] = (c4 + j <= tr) ? x[j] : 0.f;
;         *(LAS v2u*)(WL + tr * 272 + c4 * 2) = (v2u){pk2(x[0], x[1]), pk2(x[2], x[3])}; }
; #pragma unroll
;     for (int i = 0; i < 4; ++i) { const int idx = tid + 512 * i; LAS unsigned* d = (LAS unsigned*)(VL + (idx >> 4) * 260 + (idx & 15) * 16); d[0] = R.vv[i].x; d[1] = R.vv[i].y; d[2] = R.vv[i].z; d[3] = R.vv[i].w; }
;     if (tid < 128) { const float mu = R.s1 * (1.0f / DA), var = R.s2 * (1.0f / DA) - mu * mu; ST[2 * tid] = mu; ST[2 * tid + 1] = __builtin_amdgcn_rsqf(var + EPS); }
	ds_write_b64 v77, v[68:69]
	v_lshrrev_b32_e32 v77, 5, v146
	v_mov_b32_e32 v117, s15
	v_cmp_gt_u32_e64 s[10:11], v75, v77
	v_cmp_lt_u32_e64 s[14:15], v75, v77
	v_cmp_gt_u32_e64 s[16:17], v76, v77
	v_cmp_gt_u32_e64 s[18:19], v78, v77
	v_cndmask_b32_e64 v68, v80, 0, s[10:11]
	v_cndmask_b32_e64 v69, 0, v81, s[14:15]
	v_cndmask_b32_e64 v79, v82, 0, s[16:17]
	v_cndmask_b32_e64 v80, v83, 0, s[18:19]
	v_cvt_pk_bf16_f32 v68, v68, v69
	v_cvt_pk_bf16_f32 v69, v79, v80
	v_mul_u32_u24_e32 v170, 0x110, v77
	v_mad_u32_u24 v77, v77, s1, v164
	ds_write_b64 v77, v[68:69]
	v_lshrrev_b32_e32 v77, 5, v147
	v_cmp_gt_u32_e64 s[20:21], v75, v77
	v_cmp_lt_u32_e64 s[22:23], v75, v77
	v_cmp_gt_u32_e64 s[24:25], v76, v77
	v_cmp_gt_u32_e64 s[26:27], v78, v77
	v_cndmask_b32_e64 v68, v84, 0, s[20:21]
	v_cndmask_b32_e64 v69, 0, v85, s[22:23]
	v_cndmask_b32_e64 v79, v86, 0, s[24:25]
	v_cndmask_b32_e64 v80, v87, 0, s[26:27]
	v_cvt_pk_bf16_f32 v68, v68, v69
	v_cvt_pk_bf16_f32 v69, v79, v80
	v_mul_u32_u24_e32 v171, 0x110, v77
	v_mad_u32_u24 v77, v77, s1, v164
	ds_write_b64 v77, v[68:69]
	v_lshrrev_b32_e32 v77, 5, v95
	v_cmp_gt_u32_e64 s[72:73], v75, v77
	v_cmp_lt_u32_e64 s[28:29], v75, v77
	v_cmp_gt_u32_e64 s[30:31], v76, v77
	v_cmp_gt_u32_e64 s[34:35], v78, v77
	v_cndmask_b32_e64 v68, v88, 0, s[72:73]
	v_cndmask_b32_e64 v69, 0, v89, s[28:29]
	v_cndmask_b32_e64 v79, v90, 0, s[30:31]
	v_cndmask_b32_e64 v80, v91, 0, s[34:35]
	v_cvt_pk_bf16_f32 v68, v68, v69
	v_cvt_pk_bf16_f32 v69, v79, v80
	v_mul_u32_u24_e32 v172, 0x110, v77
	v_mad_u32_u24 v77, v77, s1, v164
	v_or_b32_e32 v120, 0x800, v0
	ds_write_b64 v77, v[68:69]
	v_lshrrev_b32_e32 v77, 5, v120
	v_cmp_gt_u32_e64 s[36:37], v75, v77
	v_cmp_lt_u32_e64 s[38:39], v75, v77
	v_cmp_gt_u32_e64 s[40:41], v76, v77
	v_cmp_gt_u32_e64 s[42:43], v78, v77
	v_cndmask_b32_e64 v68, v142, 0, s[36:37]
	v_cndmask_b32_e64 v69, 0, v143, s[38:39]
	v_cndmask_b32_e64 v79, v144, 0, s[40:41]
	v_cndmask_b32_e64 v80, v145, 0, s[42:43]
	v_cvt_pk_bf16_f32 v68, v68, v69
	v_cvt_pk_bf16_f32 v69, v79, v80
	v_mul_u32_u24_e32 v173, 0x110, v77
	v_mad_u32_u24 v77, v77, s1, v164
	v_or_b32_e32 v157, 0xa00, v0
	ds_write_b64 v77, v[68:69]
	v_lshrrev_b32_e32 v77, 5, v157
	v_cmp_gt_u32_e64 s[44:45], v75, v77
	v_cmp_lt_u32_e64 s[46:47], v75, v77
	v_cmp_gt_u32_e64 s[48:49], v76, v77
	v_cmp_gt_u32_e64 s[50:51], v78, v77
	v_cndmask_b32_e64 v68, v174, 0, s[44:45]
	v_cndmask_b32_e64 v69, 0, v175, s[46:47]
	v_cndmask_b32_e64 v79, v176, 0, s[48:49]
	v_cndmask_b32_e64 v80, v177, 0, s[50:51]
	v_cvt_pk_bf16_f32 v68, v68, v69
	v_cvt_pk_bf16_f32 v69, v79, v80
	v_mul_u32_u24_e32 v174, 0x110, v77
	v_mad_u32_u24 v77, v77, s1, v164
	v_or_b32_e32 v158, 0xc00, v0
	ds_write_b64 v77, v[68:69]
	v_lshrrev_b32_e32 v77, 5, v158
	v_cmp_gt_u32_e64 s[52:53], v75, v77
	v_cmp_lt_u32_e64 s[54:55], v75, v77
	v_cmp_gt_u32_e64 s[56:57], v76, v77
	v_cmp_gt_u32_e64 s[58:59], v78, v77
	v_cndmask_b32_e64 v68, v178, 0, s[52:53]
	v_cndmask_b32_e64 v69, 0, v179, s[54:55]
	v_cndmask_b32_e64 v79, v180, 0, s[56:57]
	v_cndmask_b32_e64 v80, v181, 0, s[58:59]
	v_cvt_pk_bf16_f32 v68, v68, v69
	v_cvt_pk_bf16_f32 v69, v79, v80
	v_mul_u32_u24_e32 v176, 0x110, v77
	v_mad_u32_u24 v77, v77, s1, v164
	v_or_b32_e32 v155, 0xe00, v0
	ds_write_b64 v77, v[68:69]
	v_lshrrev_b32_e32 v77, 5, v155
	v_cmp_gt_u32_e64 s[60:61], v75, v77
	v_cmp_lt_u32_e64 s[62:63], v75, v77
	v_cmp_gt_u32_e64 s[64:65], v76, v77
	v_cmp_gt_u32_e64 s[66:67], v78, v77
	v_cndmask_b32_e64 v68, v182, 0, s[60:61]
	v_cndmask_b32_e64 v69, 0, v183, s[62:63]
	v_cndmask_b32_e64 v75, v184, 0, s[64:65]
	v_cndmask_b32_e64 v76, v185, 0, s[66:67]
	v_cvt_pk_bf16_f32 v68, v68, v69
	v_cvt_pk_bf16_f32 v69, v75, v76
	v_mad_u32_u24 v75, v77, s1, v164
	ds_write_b64 v75, v[68:69]
	v_and_b32_e32 v68, 0xf0, v94
	v_add_u32_e32 v175, 0, v68
	s_movk_i32 s33, 0x104
	v_mad_u32_u24 v68, v71, s33, v175
	v_add_u32_e32 v69, 0x8800, v68
	ds_write2_b32 v69, v54, v55 offset1:1
	v_add_u32_e32 v54, 0x8808, v68
	ds_write2_b32 v54, v56, v57 offset1:1
	v_mad_u32_u24 v54, v72, s33, v175
	v_add_u32_e32 v55, 0x8800, v54
	ds_write2_b32 v55, v50, v51 offset1:1
	v_add_u32_e32 v50, 0x8808, v54
	ds_write2_b32 v50, v52, v53 offset1:1
	v_mad_u32_u24 v50, v73, s33, v175
	v_add_u32_e32 v51, 0x8800, v50
	v_add_u32_e32 v50, 0x8808, v50
	ds_write2_b32 v50, v64, v65 offset1:1
	v_mad_u32_u24 v50, v74, s33, v175
	v_mov_b32_e32 v129, 0
	v_mul_u32_u24_e32 v169, 0x110, v92
	v_mul_u32_u24_e32 v178, 0x110, v77
	v_mul_u32_u24_e32 v179, 0x104, v71
	v_mul_u32_u24_e32 v180, 0x104, v72
	v_mul_u32_u24_e32 v181, 0x104, v73
	ds_write2_b32 v51, v62, v63 offset1:1
	v_mul_u32_u24_e32 v182, 0x104, v74
	v_add_u32_e32 v51, 0x8800, v50
	v_add_u32_e32 v50, 0x8808, v50
	v_add_u32_e32 v177, 0, v70
	ds_write2_b32 v51, v58, v59 offset1:1
	ds_write2_b32 v50, v60, v61 offset1:1
	s_and_saveexec_b64 s[76:77], vcc
	s_cbranch_execz .LBB0_971
	s_waitcnt vmcnt(30)
	v_mul_f32_e32 v66, 0x3a800000, v250
	v_mul_f32_e32 v67, 0x3a800000, v251
	v_fma_f32 v50, -v67, v67, v66
	v_add_f32_e32 v50, 0x358637bd, v50
	v_rsq_f32_e32 v51, v50
	v_add_u32_e32 v52, 0x10a00, v177
	v_mov_b32_e32 v50, v67
	ds_write_b64 v52, v[50:51]
; #define LAS __attribute__((address_space(3)))
; __device__ __forceinline__ bf16x8 pack8(f32x4 lo, f32x4 hi) { v4u w; w.x = pk2(lo[0], lo[1]); w.y = pk2(lo[2], lo[3]); w.z = pk2(hi[0], hi[1]); w.w = pk2(hi[2], hi[3]); return __builtin_bit_cast(bf16x8, w); }
; __device__ __forceinline__ void gmlp_compute(GmlpRegs& R, const Args& a, const Ctx& C, int c, int hd) {
;     ...
;     const float lg = R.lg, lb = R.lb;
;     bf16x8 af[4];
; #pragma unroll
;     for (int ks = 0; ks < 4; ++ks) { f32x4 lo, hi;
; #pragma unroll
;         for (int e = 0; e < 8; ++e) { const int sl = 32 * ks + 8 * q + e;
;             const float v = __uint_as_float((unsigned)*(const LAS unsigned short*)(VL + sl * 260 + (16 * w + fr) * 2) << 16);
;             const float x = (v - ST[2 * sl]) * ST[2 * sl + 1] * lg + lb; if (e < 4) lo[e] = x; else hi[e - 4] = x; }
;         af[ks] = pack8(lo, hi); }
.LBB0_971:
	s_or_b64 exec, exec, s[76:77]
	v_or_b32_e32 v144, s2, v149
	v_lshrrev_b32_e32 v145, 4, v162
	v_lshl_add_u32 v165, v144, 1, 0
	s_movk_i32 s74, 0x820
	v_mad_u32_u24 v62, v145, s74, v165
	s_waitcnt lgkmcnt(0)
	s_barrier
	ds_read_u16 v50, v62 offset:34816
	ds_read_u16 v51, v62 offset:35076
	v_lshlrev_b32_e32 v63, 6, v145
	s_add_i32 s2, 0, 0x10a00
	v_add_u32_e32 v183, s2, v63
	s_waitcnt lgkmcnt(1)
	v_lshlrev_b32_e32 v54, 16, v50
	s_waitcnt lgkmcnt(0)
	v_lshlrev_b32_e32 v55, 16, v51
	ds_read_b128 v[50:53], v183
	v_lshlrev_b32_e32 v153, 3, v145
	v_or_b32_e32 v64, 2, v153
	v_mad_u32_u24 v65, v64, s33, v165
	s_waitcnt vmcnt(28)
	v_mov_b32_e32 v99, v98
	s_waitcnt lgkmcnt(0)
	v_mov_b32_e32 v56, v50
	v_mov_b32_e32 v57, v52
	v_pk_add_f32 v[54:55], v[54:55], v[56:57] neg_lo:[0,1] neg_hi:[0,1]
	v_mov_b32_e32 v52, v51
	v_pk_mul_f32 v[50:51], v[52:53], v[54:55]
	v_lshlrev_b32_e32 v52, 3, v64
	v_add_u32_e32 v168, s2, v52
	ds_read_u16 v52, v65 offset:34816
	ds_read_u16 v53, v62 offset:35596
	v_mov_b32_e32 v101, v100
	v_pk_fma_f32 v[50:51], v[98:99], v[50:51], v[100:101] op_sel_hi:[0,1,0]
	v_cvt_pk_bf16_f32 v50, v50, v51
	s_waitcnt lgkmcnt(1)
	v_lshlrev_b32_e32 v56, 16, v52
	s_waitcnt lgkmcnt(0)
	v_lshlrev_b32_e32 v57, 16, v53
	ds_read_b128 v[52:55], v168
	v_mul_u32_u24_e32 v167, 0x104, v64
	s_mov_b32 s74, 0x18000
	s_mov_b32 s75, 0x20000
	s_mov_b32 s76, 0x28000
	s_waitcnt lgkmcnt(0)
	v_mov_b32_e32 v58, v52
	v_mov_b32_e32 v59, v54
	v_pk_add_f32 v[56:57], v[56:57], v[58:59] neg_lo:[0,1] neg_hi:[0,1]
	v_mov_b32_e32 v54, v53
	v_pk_mul_f32 v[52:53], v[54:55], v[56:57]
	s_mov_b32 s77, 0x30000
	v_pk_fma_f32 v[56:57], v[98:99], v[52:53], v[100:101] op_sel_hi:[0,1,0]
	v_or_b32_e32 v52, 32, v63
	v_add_u32_e32 v163, s2, v52
	ds_read_u16 v52, v65 offset:35336
	ds_read_u16 v53, v62 offset:36116
	v_cvt_pk_bf16_f32 v51, v56, v57
	s_mov_b32 s78, 0x38000
	v_mul_u32_u24_e32 v184, 0x820, v145
	s_waitcnt lgkmcnt(1)
	v_lshlrev_b32_e32 v58, 16, v52
	s_waitcnt lgkmcnt(0)
	v_lshlrev_b32_e32 v59, 16, v53
	ds_read_b128 v[52:55], v163
	v_mul_u32_u24_e32 v200, 0x110, v149
	s_waitcnt lgkmcnt(0)
	v_mov_b32_e32 v60, v52
	v_mov_b32_e32 v61, v54
	v_pk_add_f32 v[58:59], v[58:59], v[60:61] neg_lo:[0,1] neg_hi:[0,1]
	v_mov_b32_e32 v54, v53
	v_pk_mul_f32 v[52:53], v[54:55], v[58:59]
	s_nop 0
	v_pk_fma_f32 v[58:59], v[98:99], v[52:53], v[100:101] op_sel_hi:[0,1,0]
	v_or_b32_e32 v52, 48, v63
	v_add_u32_e32 v166, s2, v52
	ds_read_u16 v52, v65 offset:35856
	ds_read_u16 v53, v62 offset:36636
	s_waitcnt lgkmcnt(1)
	v_lshlrev_b32_e32 v60, 16, v52
	s_waitcnt lgkmcnt(0)
	v_lshlrev_b32_e32 v61, 16, v53
	ds_read_b128 v[52:55], v166
	s_waitcnt lgkmcnt(0)
	v_mov_b32_e32 v66, v52
	v_mov_b32_e32 v67, v54
	v_pk_add_f32 v[60:61], v[60:61], v[66:67] neg_lo:[0,1] neg_hi:[0,1]
	v_mov_b32_e32 v54, v53
	v_pk_mul_f32 v[52:53], v[54:55], v[60:61]
	s_nop 0
	v_pk_fma_f32 v[54:55], v[98:99], v[52:53], v[100:101] op_sel_hi:[0,1,0]
	v_cvt_pk_bf16_f32 v53, v54, v55
	v_or_b32_e32 v54, 0x100, v63
	v_add_u32_e32 v185, s2, v54
	ds_read_u16 v54, v65 offset:42616
	ds_read_u16 v55, v62 offset:43396
	v_cvt_pk_bf16_f32 v52, v58, v59
	s_waitcnt lgkmcnt(1)
	v_lshlrev_b32_e32 v58, 16, v54
	s_waitcnt lgkmcnt(0)
	v_lshlrev_b32_e32 v59, 16, v55
	ds_read_b128 v[54:57], v185
	s_waitcnt lgkmcnt(0)
	v_mov_b32_e32 v60, v54
	v_mov_b32_e32 v61, v56
	v_pk_add_f32 v[58:59], v[58:59], v[60:61] neg_lo:[0,1] neg_hi:[0,1]
	v_mov_b32_e32 v56, v55
	v_pk_mul_f32 v[54:55], v[56:57], v[58:59]
	s_nop 0
	v_pk_fma_f32 v[58:59], v[98:99], v[54:55], v[100:101] op_sel_hi:[0,1,0]
	v_or_b32_e32 v54, 0x110, v63
	v_add_u32_e32 v186, s2, v54
	ds_read_u16 v54, v65 offset:43136
	ds_read_u16 v55, v62 offset:43916
	v_or_b32_e32 v65, 0x220, v63
	v_add_u32_e32 v192, s2, v65
	s_waitcnt lgkmcnt(1)
	v_lshlrev_b32_e32 v60, 16, v54
	s_waitcnt lgkmcnt(0)
	v_lshlrev_b32_e32 v61, 16, v55
	ds_read_b128 v[54:57], v186
	s_waitcnt lgkmcnt(0)
	v_mov_b32_e32 v66, v54
	v_mov_b32_e32 v67, v56
	v_pk_add_f32 v[60:61], v[60:61], v[66:67] neg_lo:[0,1] neg_hi:[0,1]
	v_mov_b32_e32 v56, v55
	v_pk_mul_f32 v[54:55], v[56:57], v[60:61]
	s_nop 0
	v_pk_fma_f32 v[60:61], v[98:99], v[54:55], v[100:101] op_sel_hi:[0,1,0]
	v_or_b32_e32 v54, 0x120, v63
	v_add_u32_e32 v188, s2, v54
	v_mov_b32_e32 v54, 0x2288
	v_mad_u32_u24 v54, v64, s33, v54
	v_add_u32_e32 v187, v165, v54
	ds_read_u16 v54, v187 offset:34816
	ds_read_u16 v55, v62 offset:44436
	s_waitcnt lgkmcnt(1)
	v_lshlrev_b32_e32 v66, 16, v54
	s_waitcnt lgkmcnt(0)
	v_lshlrev_b32_e32 v67, 16, v55
	ds_read_b128 v[54:57], v188
	s_waitcnt lgkmcnt(0)
	v_mov_b32_e32 v68, v54
	v_mov_b32_e32 v69, v56
	v_pk_add_f32 v[66:67], v[66:67], v[68:69] neg_lo:[0,1] neg_hi:[0,1]
	v_mov_b32_e32 v56, v55
	v_pk_mul_f32 v[54:55], v[56:57], v[66:67]
	s_nop 0
	v_pk_fma_f32 v[66:67], v[98:99], v[54:55], v[100:101] op_sel_hi:[0,1,0]
	v_or_b32_e32 v54, 0x130, v63
	v_add_u32_e32 v189, s2, v54
	ds_read_u16 v54, v187 offset:35336
	ds_read_u16 v55, v62 offset:44956
	s_waitcnt lgkmcnt(1)
	v_lshlrev_b32_e32 v68, 16, v54
	s_waitcnt lgkmcnt(0)
	v_lshlrev_b32_e32 v69, 16, v55
	ds_read_b128 v[54:57], v189
	s_waitcnt lgkmcnt(0)
	v_mov_b32_e32 v70, v54
	v_mov_b32_e32 v71, v56
	v_pk_add_f32 v[68:69], v[68:69], v[70:71] neg_lo:[0,1] neg_hi:[0,1]
	v_mov_b32_e32 v56, v55
	v_pk_mul_f32 v[54:55], v[56:57], v[68:69]
	v_cvt_pk_bf16_f32 v56, v66, v67
	v_pk_fma_f32 v[68:69], v[98:99], v[54:55], v[100:101] op_sel_hi:[0,1,0]
	v_cvt_pk_bf16_f32 v54, v58, v59
	v_or_b32_e32 v58, 0x200, v63
	v_add_u32_e32 v190, s2, v58
	ds_read_u16 v58, v187 offset:42096
	ds_read_u16 v59, v62 offset:51716
	v_cvt_pk_bf16_f32 v55, v60, v61
	v_cvt_pk_bf16_f32 v57, v68, v69
	s_waitcnt lgkmcnt(1)
; #define LAS __attribute__((address_space(3)))
; #define MFMA16(A, B, Cc) __builtin_amdgcn_mfma_f32_16x16x32_bf16((A), (B), (Cc), 0, 0, 0)
; __device__ __forceinline__ bf16x8 pack8(f32x4 lo, f32x4 hi) { v4u w; w.x = pk2(lo[0], lo[1]); w.y = pk2(lo[2], lo[3]); w.z = pk2(hi[0], hi[1]); w.w = pk2(hi[2], hi[3]); return __builtin_bit_cast(bf16x8, w); }
; __device__ __forceinline__ void gmlp_compute(GmlpRegs& R, const Args& a, const Ctx& C, int c, int hd) {
;     ...
;     bf16x8 af[4];
; #pragma unroll
;     for (int ks = 0; ks < 4; ++ks) { f32x4 lo, hi;
; #pragma unroll
;         for (int e = 0; e < 8; ++e) { const int sl = 32 * ks + 8 * q + e;
;             const float v = __uint_as_float((unsigned)*(const LAS unsigned short*)(VL + sl * 260 + (16 * w + fr) * 2) << 16);
;             const float x = (v - ST[2 * sl]) * ST[2 * sl + 1] * lg + lb; if (e < 4) lo[e] = x; else hi[e - 4] = x; }
;         af[ks] = pack8(lo, hi); }
;     f32x4 acc[8];
; #pragma unroll
;     for (int nt = 0; nt < 8; ++nt) { acc[nt] = (f32x4){0.f, 0.f, 0.f, 0.f};
; #pragma unroll
;         for (int ks = 0; ks <= nt / 2; ++ks) acc[nt] = MFMA16(af[ks], *(const LAS bf16x8*)(WL + (16 * nt + fr) * 272 + (32 * ks + 8 * q) * 2), acc[nt]); }
	v_lshlrev_b32_e32 v66, 16, v58
	s_waitcnt lgkmcnt(0)
	v_lshlrev_b32_e32 v67, 16, v59
	ds_read_b128 v[58:61], v190
	s_waitcnt lgkmcnt(0)
	v_mov_b32_e32 v68, v58
	v_mov_b32_e32 v69, v60
	v_pk_add_f32 v[66:67], v[66:67], v[68:69] neg_lo:[0,1] neg_hi:[0,1]
	v_mov_b32_e32 v60, v59
	v_pk_mul_f32 v[58:59], v[60:61], v[66:67]
	v_or_b32_e32 v60, 0x210, v63
	v_add_u32_e32 v191, s2, v60
	ds_read_u16 v60, v187 offset:42616
	ds_read_u16 v61, v62 offset:52236
	ds_read_b128 v[66:69], v191
	v_pk_fma_f32 v[58:59], v[98:99], v[58:59], v[100:101] op_sel_hi:[0,1,0]
	v_cvt_pk_bf16_f32 v58, v58, v59
	s_waitcnt lgkmcnt(2)
	v_lshlrev_b32_e32 v60, 16, v60
	s_waitcnt lgkmcnt(1)
	v_lshlrev_b32_e32 v61, 16, v61
	s_waitcnt lgkmcnt(0)
	v_mov_b32_e32 v70, v66
	ds_read_u16 v65, v187 offset:43136
	ds_read_u16 v66, v62 offset:52756
	v_mov_b32_e32 v71, v68
	v_pk_add_f32 v[60:61], v[60:61], v[70:71] neg_lo:[0,1] neg_hi:[0,1]
	v_mov_b32_e32 v68, v67
	s_waitcnt lgkmcnt(1)
	v_lshlrev_b32_e32 v70, 16, v65
	v_or_b32_e32 v65, 0x230, v63
	v_pk_mul_f32 v[60:61], v[68:69], v[60:61]
	s_waitcnt lgkmcnt(0)
	v_lshlrev_b32_e32 v71, 16, v66
	ds_read_b128 v[66:69], v192
	v_add_u32_e32 v194, s2, v65
	v_mov_b32_e32 v65, 0x4510
	v_mad_u32_u24 v64, v64, s33, v65
	v_add_u32_e32 v193, v165, v64
	ds_read_u16 v64, v193 offset:34816
	ds_read_u16 v65, v62 offset:53276
	s_waitcnt lgkmcnt(2)
	v_mov_b32_e32 v72, v66
	v_mov_b32_e32 v73, v68
	v_pk_add_f32 v[70:71], v[70:71], v[72:73] neg_lo:[0,1] neg_hi:[0,1]
	v_mov_b32_e32 v68, v67
	v_pk_mul_f32 v[66:67], v[68:69], v[70:71]
	s_waitcnt lgkmcnt(0)
	v_lshlrev_b32_e32 v71, 16, v65
	v_pk_fma_f32 v[68:69], v[98:99], v[66:67], v[100:101] op_sel_hi:[0,1,0]
	v_lshlrev_b32_e32 v70, 16, v64
	ds_read_b128 v[64:67], v194
	v_pk_fma_f32 v[60:61], v[98:99], v[60:61], v[100:101] op_sel_hi:[0,1,0]
	v_cvt_pk_bf16_f32 v59, v60, v61
	v_cvt_pk_bf16_f32 v60, v68, v69
	s_mov_b32 s33, 0x10000
	s_waitcnt lgkmcnt(0)
	v_mov_b32_e32 v72, v64
	v_mov_b32_e32 v73, v66
	v_pk_add_f32 v[70:71], v[70:71], v[72:73] neg_lo:[0,1] neg_hi:[0,1]
	v_mov_b32_e32 v66, v65
	v_pk_mul_f32 v[64:65], v[66:67], v[70:71]
	s_nop 0
	v_pk_fma_f32 v[64:65], v[98:99], v[64:65], v[100:101] op_sel_hi:[0,1,0]
	v_cvt_pk_bf16_f32 v61, v64, v65
	v_or_b32_e32 v64, 0x300, v63
	v_add_u32_e32 v195, s2, v64
	ds_read_u16 v64, v193 offset:41576
	ds_read_u16 v65, v62 offset:60036
	s_waitcnt lgkmcnt(1)
	v_lshlrev_b32_e32 v68, 16, v64
	s_waitcnt lgkmcnt(0)
	v_lshlrev_b32_e32 v69, 16, v65
	ds_read_b128 v[64:67], v195
	s_waitcnt lgkmcnt(0)
	v_mov_b32_e32 v70, v64
	v_mov_b32_e32 v71, v66
	v_pk_add_f32 v[68:69], v[68:69], v[70:71] neg_lo:[0,1] neg_hi:[0,1]
	v_mov_b32_e32 v66, v65
	v_pk_mul_f32 v[64:65], v[66:67], v[68:69]
	s_nop 0
	v_pk_fma_f32 v[68:69], v[98:99], v[64:65], v[100:101] op_sel_hi:[0,1,0]
	v_or_b32_e32 v64, 0x310, v63
	v_add_u32_e32 v196, s2, v64
	ds_read_u16 v64, v193 offset:42096
	ds_read_u16 v65, v62 offset:60556
	s_waitcnt lgkmcnt(1)
	v_lshlrev_b32_e32 v70, 16, v64
	s_waitcnt lgkmcnt(0)
	v_lshlrev_b32_e32 v71, 16, v65
	ds_read_b128 v[64:67], v196
	s_waitcnt lgkmcnt(0)
	v_mov_b32_e32 v72, v64
	v_mov_b32_e32 v73, v66
	v_pk_add_f32 v[70:71], v[70:71], v[72:73] neg_lo:[0,1] neg_hi:[0,1]
	v_mov_b32_e32 v66, v65
	v_pk_mul_f32 v[64:65], v[66:67], v[70:71]
	s_nop 0
	v_pk_fma_f32 v[70:71], v[98:99], v[64:65], v[100:101] op_sel_hi:[0,1,0]
	v_or_b32_e32 v64, 0x320, v63
	v_add_u32_e32 v197, s2, v64
	ds_read_u16 v64, v193 offset:42616
	ds_read_u16 v65, v62 offset:61076
	v_or_b32_e32 v63, 0x330, v63
	v_add_u32_e32 v198, s2, v63
	s_mov_b32 s2, 0x8000
	s_waitcnt lgkmcnt(1)
	v_lshlrev_b32_e32 v72, 16, v64
	s_waitcnt lgkmcnt(0)
	v_lshlrev_b32_e32 v73, 16, v65
	ds_read_b128 v[64:67], v197
	ds_read_u16 v63, v193 offset:43136
	ds_read_u16 v62, v62 offset:61596
	s_waitcnt lgkmcnt(2)
	v_mov_b32_e32 v74, v64
	v_mov_b32_e32 v75, v66
	v_pk_add_f32 v[72:73], v[72:73], v[74:75] neg_lo:[0,1] neg_hi:[0,1]
	v_mov_b32_e32 v66, v65
	v_pk_mul_f32 v[64:65], v[66:67], v[72:73]
	s_waitcnt lgkmcnt(0)
	v_lshlrev_b32_e32 v73, 16, v62
	v_pk_fma_f32 v[66:67], v[98:99], v[64:65], v[100:101] op_sel_hi:[0,1,0]
	v_lshlrev_b32_e32 v72, 16, v63
	ds_read_b128 v[62:65], v198
	s_waitcnt lgkmcnt(0)
	v_mov_b32_e32 v74, v62
	v_mov_b32_e32 v75, v64
	v_pk_add_f32 v[72:73], v[72:73], v[74:75] neg_lo:[0,1] neg_hi:[0,1]
	v_mov_b32_e32 v64, v63
	v_pk_mul_f32 v[62:63], v[64:65], v[72:73]
	v_cvt_pk_bf16_f32 v64, v66, v67
	v_and_b32_e32 v66, 48, v0
	v_add_u32_e32 v199, 0, v66
	v_mad_u32_u24 v112, v149, s1, v199
	v_pk_fma_f32 v[72:73], v[98:99], v[62:63], v[100:101] op_sel_hi:[0,1,0]
	v_cvt_pk_bf16_f32 v62, v68, v69
	ds_read_b128 v[66:69], v112
	v_cvt_pk_bf16_f32 v63, v70, v71
	v_cvt_pk_bf16_f32 v65, v72, v73
	ds_read_b128 v[70:73], v112 offset:8704
	s_waitcnt lgkmcnt(1)
	v_mfma_f32_16x16x32_bf16 v[78:81], v[50:53], v[66:69], 0
	ds_read_b128 v[66:69], v112 offset:4352
	ds_read_b128 v[74:77], v112 offset:8768
	ds_read_b128 v[82:85], v112 offset:13120
	s_waitcnt lgkmcnt(3)
	v_mfma_f32_16x16x32_bf16 v[70:73], v[50:53], v[70:73], 0
	ds_read_b128 v[86:89], v112 offset:17472
	ds_read_b128 v[90:93], v112 offset:21824
	ds_read_b128 v[202:205], v112 offset:26176
	s_waitcnt lgkmcnt(4)
	v_mfma_f32_16x16x32_bf16 v[70:73], v[54:57], v[74:77], v[70:73]
	ds_read_b128 v[74:77], v112 offset:13056
	s_mov_b32 s1, 0xc3e00000
	s_waitcnt lgkmcnt(0)
	v_mfma_f32_16x16x32_bf16 v[74:77], v[50:53], v[74:77], 0
	v_mfma_f32_16x16x32_bf16 v[74:77], v[54:57], v[82:85], v[74:77]
	ds_read_b128 v[82:85], v112 offset:17408
	s_waitcnt lgkmcnt(0)
	v_mfma_f32_16x16x32_bf16 v[82:85], v[50:53], v[82:85], 0
	v_mfma_f32_16x16x32_bf16 v[82:85], v[54:57], v[86:89], v[82:85]
	ds_read_b128 v[86:89], v112 offset:17536
	s_waitcnt lgkmcnt(0)
; #define LAS __attribute__((address_space(3)))
; #define MFMA16(A, B, Cc) __builtin_amdgcn_mfma_f32_16x16x32_bf16((A), (B), (Cc), 0, 0, 0)
; #define PIN(x) asm volatile("" : "+v"(x))
; __device__ __forceinline__ float bf_lo(unsigned w) { return __uint_as_float(w << 16); }
; __device__ __forceinline__ unsigned pk4f8(float a, float b, float c, float d) { int p = __builtin_amdgcn_cvt_pk_fp8_f32(sat8(a), sat8(b), 0, false); p = __builtin_amdgcn_cvt_pk_fp8_f32(sat8(c), sat8(d), p, true); return (unsigned)p; }
; __device__ __forceinline__ float bf_hi(unsigned w) { return __uint_as_float(w & 0xffff0000u); }
; __device__ __forceinline__ void gmlp_compute(GmlpRegs& R, const Args& a, const Ctx& C, int c, int hd) {
;     ...
;     for (int nt = 0; nt < 8; ++nt) { acc[nt] = (f32x4){0.f, 0.f, 0.f, 0.f};
; #pragma unroll
;         for (int ks = 0; ks <= nt / 2; ++ks) acc[nt] = MFMA16(af[ks], *(const LAS bf16x8*)(WL + (16 * nt + fr) * 272 + (32 * ks + 8 * q) * 2), acc[nt]); }
; #pragma unroll
;     for (int nt = 0; nt < 8; ++nt) PIN(R.uq[nt]);
; #pragma unroll
;     for (int nt = 0; nt < 8; ++nt) { const size_t row = T0 + 16 * nt + fr; const float bs = R.bsv[nt];
;         const float o0 = bf_lo(R.uq[nt].x) * (acc[nt][0] + bs), o1 = bf_hi(R.uq[nt].x) * (acc[nt][1] + bs);
;         const float o2 = bf_lo(R.uq[nt].y) * (acc[nt][2] + bs), o3 = bf_hi(R.uq[nt].y) * (acc[nt][3] + bs);
;         *(unsigned*)((unsigned char*)Y + row * DM + chs) = pk4f8(o0, o1, o2, o3); }
	v_mfma_f32_16x16x32_bf16 v[82:85], v[58:61], v[86:89], v[82:85]
	ds_read_b128 v[86:89], v112 offset:21760
	s_waitcnt lgkmcnt(0)
	v_mfma_f32_16x16x32_bf16 v[86:89], v[50:53], v[86:89], 0
	v_mfma_f32_16x16x32_bf16 v[86:89], v[54:57], v[90:93], v[86:89]
	ds_read_b128 v[90:93], v112 offset:21888
	s_waitcnt lgkmcnt(0)
	v_mfma_f32_16x16x32_bf16 v[86:89], v[58:61], v[90:93], v[86:89]
	ds_read_b128 v[90:93], v112 offset:26112
	s_waitcnt lgkmcnt(0)
	v_mfma_f32_16x16x32_bf16 v[90:93], v[50:53], v[90:93], 0
	v_mfma_f32_16x16x32_bf16 v[90:93], v[54:57], v[202:205], v[90:93]
	ds_read_b128 v[202:205], v112 offset:26240
	s_waitcnt lgkmcnt(0)
	v_mfma_f32_16x16x32_bf16 v[90:93], v[58:61], v[202:205], v[90:93]
	ds_read_b128 v[202:205], v112 offset:26304
	s_waitcnt lgkmcnt(0)
	v_mfma_f32_16x16x32_bf16 v[90:93], v[62:65], v[202:205], v[90:93]
	ds_read_b128 v[202:205], v112 offset:30464
	v_mfma_f32_16x16x32_bf16 v[66:69], v[50:53], v[66:69], 0
	s_waitcnt lgkmcnt(0)
	v_mfma_f32_16x16x32_bf16 v[50:53], v[50:53], v[202:205], 0
	ds_read_b128 v[202:205], v112 offset:30528
	s_waitcnt lgkmcnt(0)
	v_mfma_f32_16x16x32_bf16 v[50:53], v[54:57], v[202:205], v[50:53]
	ds_read_b128 v[54:57], v112 offset:30592
	s_waitcnt lgkmcnt(0)
	v_mfma_f32_16x16x32_bf16 v[50:53], v[58:61], v[54:57], v[50:53]
	ds_read_b128 v[54:57], v112 offset:30656
	s_waitcnt vmcnt(27)
	v_lshlrev_b32_e32 v112, 2, v145
	s_waitcnt lgkmcnt(0)
	v_mfma_f32_16x16x32_bf16 v[50:53], v[62:65], v[54:57], v[50:53]
	v_lshlrev_b32_e32 v54, 16, v140
	s_waitcnt vmcnt(19)
	v_add_f32_e32 v55, v161, v78
	v_mul_f32_e32 v54, v55, v54
	v_and_b32_e32 v55, 0xffff0000, v140
	v_add_f32_e32 v56, v161, v79
	v_or_b32_e32 v128, s0, v112
	v_mul_f32_e32 v55, v56, v55
	v_lshlrev_b32_e32 v56, 16, v141
	v_add_f32_e32 v57, v161, v80
	v_lshl_add_u64 v[142:143], s[70:71], 0, v[128:129]
	v_mul_f32_e32 v56, v57, v56
	v_and_b32_e32 v57, 0xffff0000, v141
	v_add_f32_e32 v58, v161, v81
	v_mov_b32_e32 v128, 0x43e00000
	v_mul_f32_e32 v57, v58, v57
	v_med3_f32 v54, v54, s1, v128
	v_med3_f32 v55, v55, s1, v128
	v_mov_b32_e32 v58, v129
	v_cvt_pk_fp8_f32 v58, v54, v55
	v_med3_f32 v54, v56, s1, v128
	v_med3_f32 v55, v57, s1, v128
	v_cvt_pk_fp8_f32 v58, v54, v55 op_sel:[0,0,1]
	v_lshlrev_b64 v[54:55], 11, v[136:137]
	v_lshl_add_u64 v[54:55], v[142:143], 0, v[54:55]
	v_lshlrev_b32_e32 v56, 16, v138
	s_waitcnt vmcnt(18)
	v_add_f32_e32 v57, v160, v66
	global_store_dword v[54:55], v58, off
	v_mul_f32_e32 v56, v57, v56
	v_and_b32_e32 v57, 0xffff0000, v138
	v_add_f32_e32 v58, v160, v67
	v_mul_f32_e32 v57, v58, v57
	v_lshlrev_b32_e32 v58, 16, v139
	v_add_f32_e32 v59, v160, v68
	v_mul_f32_e32 v58, v59, v58
	v_and_b32_e32 v59, 0xffff0000, v139
	v_add_f32_e32 v60, v160, v69
	v_mul_f32_e32 v59, v60, v59
	v_med3_f32 v56, v56, s1, v128
	v_med3_f32 v57, v57, s1, v128
	v_mov_b32_e32 v60, v129
	v_cvt_pk_fp8_f32 v60, v56, v57
	v_med3_f32 v56, v58, s1, v128
	v_med3_f32 v57, v59, s1, v128
	s_waitcnt vmcnt(18)
	v_add_f32_e32 v58, v159, v71
	v_cvt_pk_fp8_f32 v60, v56, v57 op_sel:[0,0,1]
	v_add_co_u32_e64 v56, s[70:71], s2, v54
	v_add_f32_e32 v59, v159, v72
	s_nop 0
	v_addc_co_u32_e64 v57, s[70:71], 0, v55, s[70:71]
	global_store_dword v[56:57], v60, off
	v_lshlrev_b32_e32 v56, 16, v134
	v_add_f32_e32 v57, v159, v70
	v_mul_f32_e32 v56, v57, v56
	v_and_b32_e32 v57, 0xffff0000, v134
	v_mul_f32_e32 v57, v58, v57
	v_lshlrev_b32_e32 v58, 16, v135
	v_mul_f32_e32 v58, v59, v58
	v_and_b32_e32 v59, 0xffff0000, v135
	v_add_f32_e32 v60, v159, v73
	v_mul_f32_e32 v59, v60, v59
	v_med3_f32 v56, v56, s1, v128
	v_med3_f32 v57, v57, s1, v128
	v_mov_b32_e32 v60, v129
	v_cvt_pk_fp8_f32 v60, v56, v57
	v_med3_f32 v56, v58, s1, v128
	v_med3_f32 v57, v59, s1, v128
	s_waitcnt vmcnt(18)
	v_add_f32_e32 v58, v156, v75
	v_cvt_pk_fp8_f32 v60, v56, v57 op_sel:[0,0,1]
	v_add_co_u32_e64 v56, s[70:71], s33, v54
	v_add_f32_e32 v59, v156, v76
	s_nop 0
	v_addc_co_u32_e64 v57, s[70:71], 0, v55, s[70:71]
	global_store_dword v[56:57], v60, off
	v_lshlrev_b32_e32 v56, 16, v132
	v_add_f32_e32 v57, v156, v74
	v_mul_f32_e32 v56, v57, v56
	v_and_b32_e32 v57, 0xffff0000, v132
	v_mul_f32_e32 v57, v58, v57
	v_lshlrev_b32_e32 v58, 16, v133
	v_mul_f32_e32 v58, v59, v58
	v_and_b32_e32 v59, 0xffff0000, v133
	v_add_f32_e32 v60, v156, v77
	v_mul_f32_e32 v59, v60, v59
	v_med3_f32 v56, v56, s1, v128
	v_med3_f32 v57, v57, s1, v128
	v_mov_b32_e32 v60, v129
	v_cvt_pk_fp8_f32 v60, v56, v57
	v_med3_f32 v56, v58, s1, v128
	v_med3_f32 v57, v59, s1, v128
	s_waitcnt vmcnt(18)
	v_add_f32_e32 v58, v154, v83
	v_cvt_pk_fp8_f32 v60, v56, v57 op_sel:[0,0,1]
	v_add_co_u32_e64 v56, s[70:71], s74, v54
	v_add_f32_e32 v59, v154, v84
	s_nop 0
	v_addc_co_u32_e64 v57, s[70:71], 0, v55, s[70:71]
	global_store_dword v[56:57], v60, off
	v_lshlrev_b32_e32 v56, 16, v130
	v_add_f32_e32 v57, v154, v82
	v_mul_f32_e32 v56, v57, v56
	v_and_b32_e32 v57, 0xffff0000, v130
	v_mul_f32_e32 v57, v58, v57
	v_lshlrev_b32_e32 v58, 16, v131
	v_mul_f32_e32 v58, v59, v58
	v_and_b32_e32 v59, 0xffff0000, v131
	v_add_f32_e32 v60, v154, v85
	v_mul_f32_e32 v59, v60, v59
	v_med3_f32 v56, v56, s1, v128
	v_med3_f32 v57, v57, s1, v128
	v_mov_b32_e32 v60, v129
	v_cvt_pk_fp8_f32 v60, v56, v57
	v_med3_f32 v56, v58, s1, v128
	v_med3_f32 v57, v59, s1, v128
	s_waitcnt vmcnt(18)
	v_add_f32_e32 v58, v152, v87
	v_cvt_pk_fp8_f32 v60, v56, v57 op_sel:[0,0,1]
	v_add_co_u32_e64 v56, s[70:71], s75, v54
	v_add_f32_e32 v59, v152, v88
	s_nop 0
	v_addc_co_u32_e64 v57, s[70:71], 0, v55, s[70:71]
	global_store_dword v[56:57], v60, off
	v_lshlrev_b32_e32 v56, 16, v126
	v_add_f32_e32 v57, v152, v86
	v_mul_f32_e32 v56, v57, v56
	v_and_b32_e32 v57, 0xffff0000, v126
	v_mul_f32_e32 v57, v58, v57
	v_lshlrev_b32_e32 v58, 16, v127
	v_mul_f32_e32 v58, v59, v58
	v_and_b32_e32 v59, 0xffff0000, v127
	v_add_f32_e32 v60, v152, v89
	v_mul_f32_e32 v59, v60, v59
	v_med3_f32 v56, v56, s1, v128
	v_med3_f32 v57, v57, s1, v128
	v_mov_b32_e32 v60, v129
	v_cvt_pk_fp8_f32 v60, v56, v57
	v_med3_f32 v56, v58, s1, v128
	v_med3_f32 v57, v59, s1, v128
	s_waitcnt vmcnt(18)
; #define LAS __attribute__((address_space(3)))
; #define PIN(x) asm volatile("" : "+v"(x))
; __device__ __forceinline__ unsigned pk2(float lo, float hi) { return pg8::cvt_pk_bf16(lo, hi); }
; __device__ __forceinline__ float bf_lo(unsigned w) { return __uint_as_float(w << 16); }
; __device__ __forceinline__ unsigned pk4f8(float a, float b, float c, float d) { int p = __builtin_amdgcn_cvt_pk_fp8_f32(sat8(a), sat8(b), 0, false); p = __builtin_amdgcn_cvt_pk_fp8_f32(sat8(c), sat8(d), p, true); return (unsigned)p; }
; __device__ __forceinline__ float bf_hi(unsigned w) { return __uint_as_float(w & 0xffff0000u); }
; __device__ __forceinline__ void gmlp_compute(GmlpRegs& R, const Args& a, const Ctx& C, int c, int hd) {
;     ...
;     for (int i = 0; i < 8; ++i) PIN(R.wv[i]);
; #pragma unroll
;     for (int i = 0; i < 4; ++i) PIN(R.vv[i]);
;     __syncthreads();
; #pragma unroll
;     for (int i = 0; i < 8; ++i) { const int idx = tid + 512 * i, tr = idx >> 5, c4 = (idx & 31) * 4; f32x4 x = R.wv[i];
; #pragma unroll
;         for (int j = 0; j < 4; ++j) x[j] = (c4 + j <= tr) ? x[j] : 0.f;
;         *(LAS v2u*)(WL + tr * 272 + c4 * 2) = (v2u){pk2(x[0], x[1]), pk2(x[2], x[3])}; }
; #pragma unroll
;     for (int i = 0; i < 4; ++i) { const int idx = tid + 512 * i; LAS unsigned* d = (LAS unsigned*)(VL + (idx >> 4) * 260 + (idx & 15) * 16); d[0] = R.vv[i].x; d[1] = R.vv[i].y; d[2] = R.vv[i].z; d[3] = R.vv[i].w; }
;     if (tid < 128) { const float mu = R.s1 * (1.0f / DA), var = R.s2 * (1.0f / DA) - mu * mu; ST[2 * tid] = mu; ST[2 * tid + 1] = __builtin_amdgcn_rsqf(var + EPS); }
;     ...
; #pragma unroll
;     for (int nt = 0; nt < 8; ++nt) { const size_t row = T0 + 16 * nt + fr; const float bs = R.bsv[nt];
;         const float o0 = bf_lo(R.uq[nt].x) * (acc[nt][0] + bs), o1 = bf_hi(R.uq[nt].x) * (acc[nt][1] + bs);
;         const float o2 = bf_lo(R.uq[nt].y) * (acc[nt][2] + bs), o3 = bf_hi(R.uq[nt].y) * (acc[nt][3] + bs);
;         *(unsigned*)((unsigned char*)Y + row * DM + chs) = pk4f8(o0, o1, o2, o3); }
	v_add_f32_e32 v58, v151, v91
	v_cvt_pk_fp8_f32 v60, v56, v57 op_sel:[0,0,1]
	v_add_co_u32_e64 v56, s[70:71], s76, v54
	v_add_f32_e32 v59, v151, v92
	s_nop 0
	v_addc_co_u32_e64 v57, s[70:71], 0, v55, s[70:71]
	global_store_dword v[56:57], v60, off
	v_lshlrev_b32_e32 v56, 16, v124
	v_add_f32_e32 v57, v151, v90
	v_mul_f32_e32 v56, v57, v56
	v_and_b32_e32 v57, 0xffff0000, v124
	v_mul_f32_e32 v57, v58, v57
	v_lshlrev_b32_e32 v58, 16, v125
	v_mul_f32_e32 v58, v59, v58
	v_and_b32_e32 v59, 0xffff0000, v125
	v_add_f32_e32 v60, v151, v93
	v_mul_f32_e32 v59, v60, v59
	v_med3_f32 v56, v56, s1, v128
	v_med3_f32 v57, v57, s1, v128
	v_mov_b32_e32 v60, v129
	v_cvt_pk_fp8_f32 v60, v56, v57
	v_med3_f32 v56, v58, s1, v128
	v_med3_f32 v57, v59, s1, v128
	s_waitcnt vmcnt(18)
	v_add_f32_e32 v50, v150, v50
	v_cvt_pk_fp8_f32 v60, v56, v57 op_sel:[0,0,1]
	v_add_co_u32_e64 v56, s[70:71], s77, v54
	v_add_f32_e32 v51, v150, v51
	s_nop 0
	v_addc_co_u32_e64 v57, s[70:71], 0, v55, s[70:71]
	global_store_dword v[56:57], v60, off
	v_lshlrev_b32_e32 v56, 16, v122
	v_mul_f32_e32 v50, v50, v56
	v_and_b32_e32 v56, 0xffff0000, v122
	v_mul_f32_e32 v51, v51, v56
	v_med3_f32 v50, v50, s1, v128
	v_med3_f32 v51, v51, s1, v128
	v_lshlrev_b32_e32 v56, 16, v123
	v_add_f32_e32 v52, v150, v52
	v_cvt_pk_fp8_f32 v129, v50, v51
	v_mul_f32_e32 v52, v52, v56
	v_and_b32_e32 v56, 0xffff0000, v123
	v_add_f32_e32 v53, v150, v53
	v_mul_f32_e32 v53, v53, v56
	v_med3_f32 v50, v52, s1, v128
	v_med3_f32 v51, v53, s1, v128
	v_cvt_pk_fp8_f32 v129, v50, v51 op_sel:[0,0,1]
	v_add_co_u32_e64 v50, s[70:71], s78, v54
	v_readlane_b32 s0, v249, 0
	s_nop 0
	v_addc_co_u32_e64 v51, s[70:71], 0, v55, s[70:71]
	s_ashr_i32 s70, s0, 6
	s_ashr_i32 s71, s70, 31
	s_and_b32 s0, s0, 63
	s_lshl_b64 s[80:81], s[70:71], 16
	s_add_u32 s79, s94, s80
	s_addc_u32 s80, s95, s81
	s_mul_i32 s81, s0, 0x42000
	s_add_u32 s79, s79, s81
	s_addc_u32 s81, s80, 0
	s_add_u32 s80, s79, 0xc200000
	global_store_dword v[50:51], v129, off
	s_addc_u32 s81, s81, 0
	v_lshlrev_b32_e32 v87, 4, v146
	v_lshlrev_b32_e32 v86, 4, v95
	v_lshlrev_b32_e32 v85, 4, v120
	v_lshlrev_b32_e32 v84, 4, v157
	v_lshlrev_b32_e32 v83, 4, v158
	v_lshlrev_b32_e32 v82, 4, v155
	global_load_dwordx4 v[74:77], v94, s[80:81] nt
	global_load_dwordx4 v[78:81], v87, s[80:81] nt
	global_load_dwordx4 v[70:73], v148, s[80:81] nt
	global_load_dwordx4 v[66:69], v86, s[80:81] nt
	global_load_dwordx4 v[58:61], v85, s[80:81] nt
	global_load_dwordx4 v[62:65], v84, s[80:81] nt
	global_load_dwordx4 v[50:53], v83, s[80:81] nt
	global_load_dwordx4 v[54:57], v82, s[80:81] nt
	s_nop 0
	v_cndmask_b32_e64 v26, v26, 0, s[68:69]
	v_cndmask_b32_e64 v27, 0, v27, s[4:5]
	v_cndmask_b32_e64 v28, v28, 0, s[6:7]
	v_cndmask_b32_e64 v29, v29, 0, s[8:9]
	v_cvt_pk_bf16_f32 v26, v26, v27
	v_cvt_pk_bf16_f32 v27, v28, v29
	v_add_u32_e32 v28, v164, v169
	s_waitcnt vmcnt(27)
	s_waitcnt vmcnt(26)
	s_waitcnt vmcnt(25)
	s_waitcnt vmcnt(24)
	s_barrier
	ds_write_b64 v28, v[26:27]
	v_cndmask_b32_e64 v26, v30, 0, s[10:11]
	v_cndmask_b32_e64 v27, 0, v31, s[14:15]
	v_cndmask_b32_e64 v28, v32, 0, s[16:17]
	v_cndmask_b32_e64 v29, v33, 0, s[18:19]
	v_cndmask_b32_e64 v18, v18, 0, s[20:21]
	v_cndmask_b32_e64 v19, 0, v19, s[22:23]
	v_cndmask_b32_e64 v20, v20, 0, s[24:25]
	v_cndmask_b32_e64 v21, v21, 0, s[26:27]
	v_cvt_pk_bf16_f32 v26, v26, v27
	v_cvt_pk_bf16_f32 v27, v28, v29
	v_add_u32_e32 v28, v164, v170
	v_cvt_pk_bf16_f32 v18, v18, v19
	v_cvt_pk_bf16_f32 v19, v20, v21
	v_add_u32_e32 v20, v164, v171
	ds_write_b64 v28, v[26:27]
	ds_write_b64 v20, v[18:19]
	v_cndmask_b32_e64 v18, v22, 0, s[72:73]
	v_cndmask_b32_e64 v19, 0, v23, s[28:29]
	v_cndmask_b32_e64 v20, v24, 0, s[30:31]
	v_cndmask_b32_e64 v21, v25, 0, s[34:35]
	v_cndmask_b32_e64 v10, v10, 0, s[36:37]
	v_cndmask_b32_e64 v11, 0, v11, s[38:39]
	v_cndmask_b32_e64 v12, v12, 0, s[40:41]
	v_cndmask_b32_e64 v13, v13, 0, s[42:43]
	v_cvt_pk_bf16_f32 v18, v18, v19
	v_cvt_pk_bf16_f32 v19, v20, v21
	v_add_u32_e32 v20, v164, v172
	v_cvt_pk_bf16_f32 v10, v10, v11
	v_cvt_pk_bf16_f32 v11, v12, v13
	v_add_u32_e32 v12, v164, v173
	ds_write_b64 v20, v[18:19]
	ds_write_b64 v12, v[10:11]
	v_cndmask_b32_e64 v10, v14, 0, s[44:45]
	v_cndmask_b32_e64 v11, 0, v15, s[46:47]
	v_cndmask_b32_e64 v12, v16, 0, s[48:49]
	v_cndmask_b32_e64 v13, v17, 0, s[50:51]
	v_cndmask_b32_e64 v6, v6, 0, s[52:53]
	v_cndmask_b32_e64 v7, 0, v7, s[54:55]
	v_cndmask_b32_e64 v8, v8, 0, s[56:57]
	v_cndmask_b32_e64 v9, v9, 0, s[58:59]
	v_cndmask_b32_e64 v2, v2, 0, s[60:61]
	v_cndmask_b32_e64 v3, 0, v3, s[62:63]
	v_cndmask_b32_e64 v4, v4, 0, s[64:65]
	v_cndmask_b32_e64 v5, v5, 0, s[66:67]
	v_cvt_pk_bf16_f32 v10, v10, v11
	v_cvt_pk_bf16_f32 v11, v12, v13
	v_add_u32_e32 v12, v164, v174
	v_cvt_pk_bf16_f32 v6, v6, v7
	v_cvt_pk_bf16_f32 v7, v8, v9
	v_add_u32_e32 v8, v164, v176
	v_cvt_pk_bf16_f32 v2, v2, v3
	v_cvt_pk_bf16_f32 v3, v4, v5
	v_add_u32_e32 v4, v164, v178
	ds_write_b64 v12, v[10:11]
	ds_write_b64 v8, v[6:7]
	ds_write_b64 v4, v[2:3]
	v_add_u32_e32 v2, v175, v179
	v_add_u32_e32 v3, 0x8800, v2
	v_add_u32_e32 v2, 0x8808, v2
	ds_write2_b32 v2, v40, v41 offset1:1
	v_add_u32_e32 v2, v175, v180
	ds_write2_b32 v3, v38, v39 offset1:1
	v_add_u32_e32 v3, 0x8800, v2
	v_add_u32_e32 v2, 0x8808, v2
	ds_write2_b32 v2, v36, v37 offset1:1
	v_add_u32_e32 v2, v175, v181
	ds_write2_b32 v3, v34, v35 offset1:1
	v_add_u32_e32 v3, 0x8800, v2
	v_add_u32_e32 v2, 0x8808, v2
	ds_write2_b32 v2, v48, v49 offset1:1
	v_add_u32_e32 v2, v175, v182
	ds_write2_b32 v3, v46, v47 offset1:1
	v_add_u32_e32 v3, 0x8800, v2
	v_add_u32_e32 v2, 0x8808, v2
	ds_write2_b32 v3, v42, v43 offset1:1
	ds_write2_b32 v2, v44, v45 offset1:1
	s_and_saveexec_b64 s[4:5], vcc
	s_cbranch_execz .LBB0_973
	s_waitcnt vmcnt(24)
	v_mul_f32_e32 v113, 0x3a800000, v252
	v_mul_f32_e32 v121, 0x3a800000, v253
	v_fma_f32 v2, -v121, v121, v113
	v_add_f32_e32 v2, 0x358637bd, v2
	v_rsq_f32_e32 v3, v2
	v_add_u32_e32 v4, 0x10a00, v177
	v_mov_b32_e32 v2, v121
	ds_write_b64 v4, v[2:3]

; __global__ void __launch_bounds__(NWAVES * 64, 2) hymba_fwd(Args args) {
	.amdhsa_kernel _Z9hymba_fwd4Args
		.amdhsa_group_segment_fixed_size 0
		.amdhsa_private_segment_fixed_size 0
		.amdhsa_kernarg_size 488
		.amdhsa_user_sgpr_count 2
		.amdhsa_user_sgpr_dispatch_ptr 0
		.amdhsa_user_sgpr_queue_ptr 0
		.amdhsa_user_sgpr_kernarg_segment_ptr 1
		.amdhsa_user_sgpr_dispatch_id 0
		.amdhsa_user_sgpr_kernarg_preload_length 0
		.amdhsa_user_sgpr_kernarg_preload_offset 0
		.amdhsa_user_sgpr_private_segment_size 0
		.amdhsa_uses_dynamic_stack 0
		.amdhsa_enable_private_segment 0
		.amdhsa_system_sgpr_workgroup_id_x 1
		.amdhsa_system_sgpr_workgroup_id_y 0
		.amdhsa_system_sgpr_workgroup_id_z 0
		.amdhsa_system_sgpr_workgroup_info 0
		.amdhsa_system_vgpr_workitem_id 0
		.amdhsa_next_free_vgpr 256
		.amdhsa_next_free_sgpr 98
		.amdhsa_accum_offset 256
		.amdhsa_reserve_vcc 1
		.amdhsa_float_round_mode_32 0
		.amdhsa_float_round_mode_16_64 0
		.amdhsa_float_denorm_mode_32 3
		.amdhsa_float_denorm_mode_16_64 3
		.amdhsa_dx10_clamp 1
		.amdhsa_ieee_mode 1
		.amdhsa_fp16_overflow 0
		.amdhsa_tg_split 0
		.amdhsa_exception_fp_ieee_invalid_op 0
		.amdhsa_exception_fp_denorm_src 0
		.amdhsa_exception_fp_ieee_div_zero 0
		.amdhsa_exception_fp_ieee_overflow 0
		.amdhsa_exception_fp_ieee_underflow 0
		.amdhsa_exception_fp_ieee_inexact 0
		.amdhsa_exception_int_div_zero 0
	.end_amdhsa_kernel

; __global__ void __launch_bounds__(NWAVES * 64, 2) hymba_fwd(Args args) {
amdhsa.kernels:
  - .agpr_count:     0
    .args:
      - .offset:         0
        .size:           232
        .value_kind:     by_value
      - .offset:         232
        .size:           4
        .value_kind:     hidden_block_count_x
      - .offset:         236
        .size:           4
        .value_kind:     hidden_block_count_y
      - .offset:         240
        .size:           4
        .value_kind:     hidden_block_count_z
      - .offset:         244
        .size:           2
        .value_kind:     hidden_group_size_x
      - .offset:         246
        .size:           2
        .value_kind:     hidden_group_size_y
      - .offset:         248
        .size:           2
        .value_kind:     hidden_group_size_z
      - .offset:         250
        .size:           2
        .value_kind:     hidden_remainder_x
      - .offset:         252
        .size:           2
        .value_kind:     hidden_remainder_y
      - .offset:         254
        .size:           2
        .value_kind:     hidden_remainder_z
      - .offset:         272
        .size:           8
        .value_kind:     hidden_global_offset_x
      - .offset:         280
        .size:           8
        .value_kind:     hidden_global_offset_y
      - .offset:         288
        .size:           8
        .value_kind:     hidden_global_offset_z
      - .offset:         296
        .size:           2
        .value_kind:     hidden_grid_dims
      - .offset:         352
        .size:           4
        .value_kind:     hidden_dynamic_lds_size
    .group_segment_fixed_size: 0
    .kernarg_segment_align: 8
    .kernarg_segment_size: 488
    .language:       OpenCL C
    .language_version:
      - 2
      - 0
    .max_flat_workgroup_size: 512
    .name:           _Z9hymba_fwd4Args
    .private_segment_fixed_size: 0
    .sgpr_count:     104
    .sgpr_spill_count: 70
    .symbol:         _Z9hymba_fwd4Args.kd
    .uniform_work_group_size: 1
    .uses_dynamic_stack: false
    .vgpr_count:     256
    .vgpr_spill_count: 0
    .wavefront_size: 64
